# S5: carry-in prefetch during previous epilogue, scan/fix-up emitted column-wise for ILP, gelu constants folded (same f32 math)
# speedup vs baseline: 1.0401x; 1.0004x over previous
.LBB0_283:
	s_or_b64 exec, exec, s[6:7]
	s_add_u32 s10, s74, 0x12cd5c00
	s_addc_u32 s11, s75, 0
	s_add_u32 s24, s74, 0x12ce5c00
	s_addc_u32 s25, s75, 0
	s_add_u32 s26, s74, 0x12d25c00
	s_addc_u32 s27, s75, 0
	s_add_u32 s28, s74, 0x12da5c00
	s_addc_u32 s29, s75, 0
	v_mov_b32_e32 v116, v174
	s_cmpk_gt_i32 s2, 0x7ff
	s_barrier
	s_cbranch_scc1 .LBB0_300
	v_and_b32_e32 v196, 63, v174
	v_lshrrev_b32_e32 v197, 6, v174
	v_and_b32_e32 v198, 31, v196
	v_lshrrev_b32_e32 v199, 5, v196
	s_and_b32 s80, s2, 7
	v_lshl_add_u32 v200, s80, 3, v197
	v_lshl_add_u32 v201, v200, 6, v198
	v_lshlrev_b32_e32 v202, 6, v201
	v_lshl_add_u32 v202, v199, 5, v202
	global_load_dwordx4 v[24:27], v202, s[24:25] offset:0
	global_load_dwordx4 v[28:31], v202, s[24:25] offset:16
	global_load_dwordx4 v[40:43], v202, s[24:25] offset:2048
	global_load_dwordx4 v[44:47], v202, s[24:25] offset:2064
	global_load_dwordx4 v[32:35], v202, s[26:27] offset:0
	global_load_dwordx4 v[36:39], v202, s[26:27] offset:16
	global_load_dwordx4 v[48:51], v202, s[26:27] offset:2048
	global_load_dwordx4 v[52:55], v202, s[26:27] offset:2064
	v_lshlrev_b32_e32 v203, 3, v201
	s_lshl_b32 s81, s80, 7
	v_lshl_add_u32 v204, v197, 4, s81
	v_lshl_add_u32 v204, v199, 3, v204
	v_lshlrev_b32_e32 v204, 2, v204
	global_load_dwordx4 v[140:143], v204, s[42:43]
	global_load_dwordx4 v[144:147], v204, s[42:43] offset:16
	v_lshl_add_u32 v205, v198, 12, v204
	v_lshlrev_b32_e32 v206, 2, v198
	v_lshl_add_u32 v207, v200, 6, v196
	v_lshlrev_b32_e32 v207, 3, v207
	v_mov_b32_e32 v254, 0x358637bd
	s_mov_b32 s8, 0
	s_mov_b32 s9, -1
	global_load_dwordx2 v[0:1], v203, s[10:11]
	global_load_dwordx2 v[2:3], v203, s[10:11] offset:256
	s_waitcnt vmcnt(0)
	v_mul_f32_e32 v58, v1, v1
	v_mul_f32_e32 v59, v1, v0
	v_fma_f32 v4, v0, v0, -v58
	v_fma_f32 v5, v0, v1, v59
	v_mul_f32_e32 v128, v3, v3
	v_mul_f32_e32 v129, v3, v2
	v_fma_f32 v6, v2, v2, -v128
	v_fma_f32 v7, v2, v3, v129
	v_mul_f32_e32 v58, v5, v5
	v_mul_f32_e32 v59, v5, v4
	v_fma_f32 v8, v4, v4, -v58
	v_fma_f32 v9, v4, v5, v59
	v_mul_f32_e32 v128, v7, v7
	v_mul_f32_e32 v129, v7, v6
	v_fma_f32 v10, v6, v6, -v128
	v_fma_f32 v11, v6, v7, v129
	v_mul_f32_e32 v58, v9, v9
	v_mul_f32_e32 v59, v9, v8
	v_fma_f32 v14, v8, v8, -v58
	v_fma_f32 v15, v8, v9, v59
	v_mul_f32_e32 v128, v11, v11
	v_mul_f32_e32 v129, v11, v10
	v_fma_f32 v16, v10, v10, -v128
	v_fma_f32 v17, v10, v11, v129
	v_mul_f32_e32 v58, v15, v15
	v_mul_f32_e32 v59, v15, v14
	v_fma_f32 v156, v14, v14, -v58
	v_fma_f32 v157, v14, v15, v59
	v_mul_f32_e32 v128, v17, v17
	v_mul_f32_e32 v129, v17, v16
	v_fma_f32 v158, v16, v16, -v128
	v_fma_f32 v159, v16, v17, v129
	v_mul_f32_e32 v58, v157, v157
	v_mul_f32_e32 v59, v157, v156
	v_fma_f32 v160, v156, v156, -v58
	v_fma_f32 v161, v156, v157, v59
	v_mul_f32_e32 v128, v159, v159
	v_mul_f32_e32 v129, v159, v158
	v_fma_f32 v164, v158, v158, -v128
	v_fma_f32 v165, v158, v159, v129
	s_mov_b32 s82, s2
	s_lshr_b32 s4, s82, 10
	s_bfe_u32 s6, s82, 0x70003
	s_lshl_b32 s4, s4, 13
	s_lshl_b32 s6, s6, 6
	s_add_i32 s31, s4, s6
	s_lshl_b32 s6, s31, 12
	s_add_u32 s84, s38, s6
	s_addc_u32 s85, s39, 0
	s_add_u32 s88, s84, 0x20000
	s_addc_u32 s89, s85, 0
	s_lshl_b32 s6, s31, 2
	s_add_u32 s86, s22, s6
	s_addc_u32 s87, s23, 0
	global_load_dwordx4 v[178:181], v205, s[84:85]
	global_load_dwordx4 v[182:185], v205, s[84:85] offset:16
	global_load_dword v194, v206, s[86:87]
	global_load_dwordx4 v[186:189], v205, s[88:89]
	global_load_dwordx4 v[190:193], v205, s[88:89] offset:16
	global_load_dword v195, v206, s[86:87] offset:128
.Ls5a_item:
	s_add_i32 s83, s82, 0x100
	s_cmpk_gt_i32 s83, 0x7ff
	s_cselect_b32 s83, s82, s83
	s_lshr_b32 s4, s83, 10
	s_bfe_u32 s6, s83, 0x70003
	s_lshl_b32 s4, s4, 13
	s_lshl_b32 s6, s6, 6
	s_add_i32 s32, s4, s6
	s_lshl_b32 s6, s32, 12
	s_add_u32 s90, s38, s6
	s_addc_u32 s91, s39, 0
	s_add_u32 s94, s90, 0x20000
	s_addc_u32 s95, s91, 0
	s_lshl_b32 s6, s32, 2
	s_add_u32 s92, s22, s6
	s_addc_u32 s93, s23, 0
	v_mov_b32_e32 v18, 0
	v_mov_b32_e32 v19, 0
	v_mov_b32_e32 v22, 0
	v_mov_b32_e32 v23, 0
	s_waitcnt vmcnt(3)
	v_fmamk_f32 v56, v194, 0x3a800000, v254
	v_rsq_f32_e32 v56, v56
	s_nop 0
	v_pk_mul_f32 v[148:149], v[178:179], v[56:57] op_sel_hi:[1,0]
	v_pk_mul_f32 v[150:151], v[180:181], v[56:57] op_sel_hi:[1,0]
	v_pk_mul_f32 v[152:153], v[182:183], v[56:57] op_sel_hi:[1,0]
	v_pk_mul_f32 v[154:155], v[184:185], v[56:57] op_sel_hi:[1,0]
	v_pk_mul_f32 v[148:149], v[140:141], v[148:149]
	v_pk_mul_f32 v[150:151], v[142:143], v[150:151]
	v_pk_mul_f32 v[152:153], v[144:145], v[152:153]
	v_pk_mul_f32 v[154:155], v[146:147], v[154:155]
	global_load_dwordx4 v[178:181], v205, s[90:91]
	global_load_dwordx4 v[182:185], v205, s[90:91] offset:16
	global_load_dword v194, v206, s[92:93]
	s_nop 1
	v_mfma_f32_32x32x2_f32 v[64:79], v148, v24, 0
	v_mfma_f32_32x32x2_f32 v[80:95], v148, v32, 0
	v_mfma_f32_32x32x2_f32 v[96:111], v148, v40, 0
	v_mfma_f32_32x32x2_f32 v[112:127], v148, v48, 0
	v_mfma_f32_32x32x2_f32 v[64:79], v149, v25, v[64:79]
	v_mfma_f32_32x32x2_f32 v[80:95], v149, v33, v[80:95]
	v_mfma_f32_32x32x2_f32 v[96:111], v149, v41, v[96:111]
	v_mfma_f32_32x32x2_f32 v[112:127], v149, v49, v[112:127]
	v_mfma_f32_32x32x2_f32 v[64:79], v150, v26, v[64:79]
	v_mfma_f32_32x32x2_f32 v[80:95], v150, v34, v[80:95]
	v_mfma_f32_32x32x2_f32 v[96:111], v150, v42, v[96:111]
	v_mfma_f32_32x32x2_f32 v[112:127], v150, v50, v[112:127]
	v_mfma_f32_32x32x2_f32 v[64:79], v151, v27, v[64:79]
	v_mfma_f32_32x32x2_f32 v[80:95], v151, v35, v[80:95]
	v_mfma_f32_32x32x2_f32 v[96:111], v151, v43, v[96:111]
	v_mfma_f32_32x32x2_f32 v[112:127], v151, v51, v[112:127]
	v_mfma_f32_32x32x2_f32 v[64:79], v152, v28, v[64:79]
	v_mfma_f32_32x32x2_f32 v[80:95], v152, v36, v[80:95]
	v_mfma_f32_32x32x2_f32 v[96:111], v152, v44, v[96:111]
	v_mfma_f32_32x32x2_f32 v[112:127], v152, v52, v[112:127]
	v_mfma_f32_32x32x2_f32 v[64:79], v153, v29, v[64:79]
	v_mfma_f32_32x32x2_f32 v[80:95], v153, v37, v[80:95]
	v_mfma_f32_32x32x2_f32 v[96:111], v153, v45, v[96:111]
	v_mfma_f32_32x32x2_f32 v[112:127], v153, v53, v[112:127]
	v_mfma_f32_32x32x2_f32 v[64:79], v154, v30, v[64:79]
	v_mfma_f32_32x32x2_f32 v[80:95], v154, v38, v[80:95]
	v_mfma_f32_32x32x2_f32 v[96:111], v154, v46, v[96:111]
	v_mfma_f32_32x32x2_f32 v[112:127], v154, v54, v[112:127]
	v_mfma_f32_32x32x2_f32 v[64:79], v155, v31, v[64:79]
	v_mfma_f32_32x32x2_f32 v[80:95], v155, v39, v[80:95]
	v_mfma_f32_32x32x2_f32 v[96:111], v155, v47, v[96:111]
	v_mfma_f32_32x32x2_f32 v[112:127], v155, v55, v[112:127]
	s_nop 7
	s_nop 7
	s_nop 1
	v_fmac_f32_e32 v65, v64, v0
	v_fmac_f32_e32 v97, v96, v2
	v_fmac_f32_e32 v69, v68, v0
	v_fmac_f32_e32 v101, v100, v2
	v_fmac_f32_e32 v73, v72, v0
	v_fmac_f32_e32 v105, v104, v2
	v_fmac_f32_e32 v77, v76, v0
	v_fmac_f32_e32 v109, v108, v2
	v_fmac_f32_e32 v81, v64, v1
	v_fmac_f32_e32 v113, v96, v3
	v_fmac_f32_e32 v85, v68, v1
	v_fmac_f32_e32 v117, v100, v3
	v_fmac_f32_e32 v89, v72, v1
	v_fmac_f32_e32 v121, v104, v3
	v_fmac_f32_e32 v93, v76, v1
	v_fmac_f32_e32 v125, v108, v3
	v_fma_f32 v65, -v80, v1, v65
	v_fma_f32 v97, -v112, v3, v97
	v_fma_f32 v69, -v84, v1, v69
	v_fma_f32 v101, -v116, v3, v101
	v_fma_f32 v73, -v88, v1, v73
	v_fma_f32 v105, -v120, v3, v105
	v_fma_f32 v77, -v92, v1, v77
	v_fma_f32 v109, -v124, v3, v109
	v_fmac_f32_e32 v81, v80, v0
	v_fmac_f32_e32 v113, v112, v2
	v_fmac_f32_e32 v85, v84, v0
	v_fmac_f32_e32 v117, v116, v2
	v_fmac_f32_e32 v89, v88, v0
	v_fmac_f32_e32 v121, v120, v2
	v_fmac_f32_e32 v93, v92, v0
	v_fmac_f32_e32 v125, v124, v2
	v_fmac_f32_e32 v66, v65, v0
	v_fmac_f32_e32 v98, v97, v2
	v_fmac_f32_e32 v70, v69, v0
	v_fmac_f32_e32 v102, v101, v2
	v_fmac_f32_e32 v74, v73, v0
	v_fmac_f32_e32 v106, v105, v2
	v_fmac_f32_e32 v78, v77, v0
	v_fmac_f32_e32 v110, v109, v2
	v_fmac_f32_e32 v82, v65, v1
	v_fmac_f32_e32 v114, v97, v3
	v_fmac_f32_e32 v86, v69, v1
	v_fmac_f32_e32 v118, v101, v3
	v_fmac_f32_e32 v90, v73, v1
	v_fmac_f32_e32 v122, v105, v3
	v_fmac_f32_e32 v94, v77, v1
	v_fmac_f32_e32 v126, v109, v3
	v_fma_f32 v66, -v81, v1, v66
	v_fma_f32 v98, -v113, v3, v98
	v_fma_f32 v70, -v85, v1, v70
	v_fma_f32 v102, -v117, v3, v102
	v_fma_f32 v74, -v89, v1, v74
	v_fma_f32 v106, -v121, v3, v106
	v_fma_f32 v78, -v93, v1, v78
	v_fma_f32 v110, -v125, v3, v110
	v_fmac_f32_e32 v82, v81, v0
	v_fmac_f32_e32 v114, v113, v2
	v_fmac_f32_e32 v86, v85, v0
	v_fmac_f32_e32 v118, v117, v2
	v_fmac_f32_e32 v90, v89, v0
	v_fmac_f32_e32 v122, v121, v2
	v_fmac_f32_e32 v94, v93, v0
	v_fmac_f32_e32 v126, v125, v2
	v_fmac_f32_e32 v67, v66, v0
	v_fmac_f32_e32 v99, v98, v2
	v_fmac_f32_e32 v71, v70, v0
	v_fmac_f32_e32 v103, v102, v2
	v_fmac_f32_e32 v75, v74, v0
	v_fmac_f32_e32 v107, v106, v2
	v_fmac_f32_e32 v79, v78, v0
	v_fmac_f32_e32 v111, v110, v2
	v_fmac_f32_e32 v83, v66, v1
	v_fmac_f32_e32 v115, v98, v3
	v_fmac_f32_e32 v87, v70, v1
	v_fmac_f32_e32 v119, v102, v3
	v_fmac_f32_e32 v91, v74, v1
	v_fmac_f32_e32 v123, v106, v3
	v_fmac_f32_e32 v95, v78, v1
	v_fmac_f32_e32 v127, v110, v3
	v_fma_f32 v67, -v82, v1, v67
	v_fma_f32 v99, -v114, v3, v99
	v_fma_f32 v71, -v86, v1, v71
	v_fma_f32 v103, -v118, v3, v103
	v_fma_f32 v75, -v90, v1, v75
	v_fma_f32 v107, -v122, v3, v107
	v_fma_f32 v79, -v94, v1, v79
	v_fma_f32 v111, -v126, v3, v111
	v_fmac_f32_e32 v83, v82, v0
	v_fmac_f32_e32 v115, v114, v2
	v_fmac_f32_e32 v87, v86, v0
	v_fmac_f32_e32 v119, v118, v2
	v_fmac_f32_e32 v91, v90, v0
	v_fmac_f32_e32 v123, v122, v2
	v_fmac_f32_e32 v95, v94, v0
	v_fmac_f32_e32 v127, v126, v2
	v_fmac_f32_e32 v71, v67, v14
	v_fmac_f32_e32 v103, v99, v16
	v_fmac_f32_e32 v79, v75, v14
	v_fmac_f32_e32 v111, v107, v16
	v_fmac_f32_e32 v87, v67, v15
	v_fmac_f32_e32 v119, v99, v17
	v_fmac_f32_e32 v95, v75, v15
	v_fmac_f32_e32 v127, v107, v17
	v_fma_f32 v71, -v83, v15, v71
	v_fma_f32 v103, -v115, v17, v103
	v_fma_f32 v79, -v91, v15, v79
	v_fma_f32 v111, -v123, v17, v111
	v_fmac_f32_e32 v87, v83, v14
	v_fmac_f32_e32 v119, v115, v16
	v_fmac_f32_e32 v95, v91, v14
	v_fmac_f32_e32 v127, v123, v16
	v_fmac_f32_e32 v79, v71, v156
	v_fmac_f32_e32 v111, v103, v158
	v_fmac_f32_e32 v95, v71, v157
	v_fmac_f32_e32 v127, v103, v159
	v_fma_f32 v79, -v87, v157, v79
	v_fma_f32 v111, -v119, v159, v111
	v_fmac_f32_e32 v95, v87, v156
	v_fmac_f32_e32 v127, v119, v158
	v_fma_f32 v58, v18, v160, v79
	v_fma_f32 v128, v22, v164, v111
	v_fma_f32 v59, v18, v161, v95
	v_fma_f32 v129, v22, v165, v127
	v_fma_f32 v18, -v19, v161, v58
	v_fma_f32 v22, -v23, v165, v128
	v_fma_f32 v19, v19, v160, v59
	v_fma_f32 v23, v23, v164, v129
	s_waitcnt vmcnt(3)
	v_fmamk_f32 v56, v195, 0x3a800000, v254
	v_rsq_f32_e32 v56, v56
	s_nop 0
	v_pk_mul_f32 v[148:149], v[186:187], v[56:57] op_sel_hi:[1,0]
	v_pk_mul_f32 v[150:151], v[188:189], v[56:57] op_sel_hi:[1,0]
	v_pk_mul_f32 v[152:153], v[190:191], v[56:57] op_sel_hi:[1,0]
	v_pk_mul_f32 v[154:155], v[192:193], v[56:57] op_sel_hi:[1,0]
	v_pk_mul_f32 v[148:149], v[140:141], v[148:149]
	v_pk_mul_f32 v[150:151], v[142:143], v[150:151]
	v_pk_mul_f32 v[152:153], v[144:145], v[152:153]
	v_pk_mul_f32 v[154:155], v[146:147], v[154:155]
	global_load_dwordx4 v[186:189], v205, s[94:95]
	global_load_dwordx4 v[190:193], v205, s[94:95] offset:16
	global_load_dword v195, v206, s[92:93] offset:128
	s_nop 1
	v_mfma_f32_32x32x2_f32 v[64:79], v148, v24, 0
	v_mfma_f32_32x32x2_f32 v[80:95], v148, v32, 0
	v_mfma_f32_32x32x2_f32 v[96:111], v148, v40, 0
	v_mfma_f32_32x32x2_f32 v[112:127], v148, v48, 0
	v_mfma_f32_32x32x2_f32 v[64:79], v149, v25, v[64:79]
	v_mfma_f32_32x32x2_f32 v[80:95], v149, v33, v[80:95]
	v_mfma_f32_32x32x2_f32 v[96:111], v149, v41, v[96:111]
	v_mfma_f32_32x32x2_f32 v[112:127], v149, v49, v[112:127]
	v_mfma_f32_32x32x2_f32 v[64:79], v150, v26, v[64:79]
	v_mfma_f32_32x32x2_f32 v[80:95], v150, v34, v[80:95]
	v_mfma_f32_32x32x2_f32 v[96:111], v150, v42, v[96:111]
	v_mfma_f32_32x32x2_f32 v[112:127], v150, v50, v[112:127]
	v_mfma_f32_32x32x2_f32 v[64:79], v151, v27, v[64:79]
	v_mfma_f32_32x32x2_f32 v[80:95], v151, v35, v[80:95]
	v_mfma_f32_32x32x2_f32 v[96:111], v151, v43, v[96:111]
	v_mfma_f32_32x32x2_f32 v[112:127], v151, v51, v[112:127]
	v_mfma_f32_32x32x2_f32 v[64:79], v152, v28, v[64:79]
	v_mfma_f32_32x32x2_f32 v[80:95], v152, v36, v[80:95]
	v_mfma_f32_32x32x2_f32 v[96:111], v152, v44, v[96:111]
	v_mfma_f32_32x32x2_f32 v[112:127], v152, v52, v[112:127]
	v_mfma_f32_32x32x2_f32 v[64:79], v153, v29, v[64:79]
	v_mfma_f32_32x32x2_f32 v[80:95], v153, v37, v[80:95]
	v_mfma_f32_32x32x2_f32 v[96:111], v153, v45, v[96:111]
	v_mfma_f32_32x32x2_f32 v[112:127], v153, v53, v[112:127]
	v_mfma_f32_32x32x2_f32 v[64:79], v154, v30, v[64:79]
	v_mfma_f32_32x32x2_f32 v[80:95], v154, v38, v[80:95]
	v_mfma_f32_32x32x2_f32 v[96:111], v154, v46, v[96:111]
	v_mfma_f32_32x32x2_f32 v[112:127], v154, v54, v[112:127]
	v_mfma_f32_32x32x2_f32 v[64:79], v155, v31, v[64:79]
	v_mfma_f32_32x32x2_f32 v[80:95], v155, v39, v[80:95]
	v_mfma_f32_32x32x2_f32 v[96:111], v155, v47, v[96:111]
	v_mfma_f32_32x32x2_f32 v[112:127], v155, v55, v[112:127]
	s_nop 7
	s_nop 7
	s_nop 1
	v_fmac_f32_e32 v65, v64, v0
	v_fmac_f32_e32 v97, v96, v2
	v_fmac_f32_e32 v69, v68, v0
	v_fmac_f32_e32 v101, v100, v2
	v_fmac_f32_e32 v73, v72, v0
	v_fmac_f32_e32 v105, v104, v2
	v_fmac_f32_e32 v77, v76, v0
	v_fmac_f32_e32 v109, v108, v2
	v_fmac_f32_e32 v81, v64, v1
	v_fmac_f32_e32 v113, v96, v3
	v_fmac_f32_e32 v85, v68, v1
	v_fmac_f32_e32 v117, v100, v3
	v_fmac_f32_e32 v89, v72, v1
	v_fmac_f32_e32 v121, v104, v3
	v_fmac_f32_e32 v93, v76, v1
	v_fmac_f32_e32 v125, v108, v3
	v_fma_f32 v65, -v80, v1, v65
	v_fma_f32 v97, -v112, v3, v97
	v_fma_f32 v69, -v84, v1, v69
	v_fma_f32 v101, -v116, v3, v101
	v_fma_f32 v73, -v88, v1, v73
	v_fma_f32 v105, -v120, v3, v105
	v_fma_f32 v77, -v92, v1, v77
	v_fma_f32 v109, -v124, v3, v109
	v_fmac_f32_e32 v81, v80, v0
	v_fmac_f32_e32 v113, v112, v2
	v_fmac_f32_e32 v85, v84, v0
	v_fmac_f32_e32 v117, v116, v2
	v_fmac_f32_e32 v89, v88, v0
	v_fmac_f32_e32 v121, v120, v2
	v_fmac_f32_e32 v93, v92, v0
	v_fmac_f32_e32 v125, v124, v2
	v_fmac_f32_e32 v66, v65, v0
	v_fmac_f32_e32 v98, v97, v2
	v_fmac_f32_e32 v70, v69, v0
	v_fmac_f32_e32 v102, v101, v2
	v_fmac_f32_e32 v74, v73, v0
	v_fmac_f32_e32 v106, v105, v2
	v_fmac_f32_e32 v78, v77, v0
	v_fmac_f32_e32 v110, v109, v2
	v_fmac_f32_e32 v82, v65, v1
	v_fmac_f32_e32 v114, v97, v3
	v_fmac_f32_e32 v86, v69, v1
	v_fmac_f32_e32 v118, v101, v3
	v_fmac_f32_e32 v90, v73, v1
	v_fmac_f32_e32 v122, v105, v3
	v_fmac_f32_e32 v94, v77, v1
	v_fmac_f32_e32 v126, v109, v3
	v_fma_f32 v66, -v81, v1, v66
	v_fma_f32 v98, -v113, v3, v98
	v_fma_f32 v70, -v85, v1, v70
	v_fma_f32 v102, -v117, v3, v102
	v_fma_f32 v74, -v89, v1, v74
	v_fma_f32 v106, -v121, v3, v106
	v_fma_f32 v78, -v93, v1, v78
	v_fma_f32 v110, -v125, v3, v110
	v_fmac_f32_e32 v82, v81, v0
	v_fmac_f32_e32 v114, v113, v2
	v_fmac_f32_e32 v86, v85, v0
	v_fmac_f32_e32 v118, v117, v2
	v_fmac_f32_e32 v90, v89, v0
	v_fmac_f32_e32 v122, v121, v2
	v_fmac_f32_e32 v94, v93, v0
	v_fmac_f32_e32 v126, v125, v2
	v_fmac_f32_e32 v67, v66, v0
	v_fmac_f32_e32 v99, v98, v2
	v_fmac_f32_e32 v71, v70, v0
	v_fmac_f32_e32 v103, v102, v2
	v_fmac_f32_e32 v75, v74, v0
	v_fmac_f32_e32 v107, v106, v2
	v_fmac_f32_e32 v79, v78, v0
	v_fmac_f32_e32 v111, v110, v2
	v_fmac_f32_e32 v83, v66, v1
	v_fmac_f32_e32 v115, v98, v3
	v_fmac_f32_e32 v87, v70, v1
	v_fmac_f32_e32 v119, v102, v3
	v_fmac_f32_e32 v91, v74, v1
	v_fmac_f32_e32 v123, v106, v3
	v_fmac_f32_e32 v95, v78, v1
	v_fmac_f32_e32 v127, v110, v3
	v_fma_f32 v67, -v82, v1, v67
	v_fma_f32 v99, -v114, v3, v99
	v_fma_f32 v71, -v86, v1, v71
	v_fma_f32 v103, -v118, v3, v103
	v_fma_f32 v75, -v90, v1, v75
	v_fma_f32 v107, -v122, v3, v107
	v_fma_f32 v79, -v94, v1, v79
	v_fma_f32 v111, -v126, v3, v111
	v_fmac_f32_e32 v83, v82, v0
	v_fmac_f32_e32 v115, v114, v2
	v_fmac_f32_e32 v87, v86, v0
	v_fmac_f32_e32 v119, v118, v2
	v_fmac_f32_e32 v91, v90, v0
	v_fmac_f32_e32 v123, v122, v2
	v_fmac_f32_e32 v95, v94, v0
	v_fmac_f32_e32 v127, v126, v2
	v_fmac_f32_e32 v71, v67, v14
	v_fmac_f32_e32 v103, v99, v16
	v_fmac_f32_e32 v79, v75, v14
	v_fmac_f32_e32 v111, v107, v16
	v_fmac_f32_e32 v87, v67, v15
	v_fmac_f32_e32 v119, v99, v17
	v_fmac_f32_e32 v95, v75, v15
	v_fmac_f32_e32 v127, v107, v17
	v_fma_f32 v71, -v83, v15, v71
	v_fma_f32 v103, -v115, v17, v103
	v_fma_f32 v79, -v91, v15, v79
	v_fma_f32 v111, -v123, v17, v111
	v_fmac_f32_e32 v87, v83, v14
	v_fmac_f32_e32 v119, v115, v16
	v_fmac_f32_e32 v95, v91, v14
	v_fmac_f32_e32 v127, v123, v16
	v_fmac_f32_e32 v79, v71, v156
	v_fmac_f32_e32 v111, v103, v158
	v_fmac_f32_e32 v95, v71, v157
	v_fmac_f32_e32 v127, v103, v159
	v_fma_f32 v79, -v87, v157, v79
	v_fma_f32 v111, -v119, v159, v111
	v_fmac_f32_e32 v95, v87, v156
	v_fmac_f32_e32 v127, v119, v158
	v_fma_f32 v58, v18, v160, v79
	v_fma_f32 v128, v22, v164, v111
	v_fma_f32 v59, v18, v161, v95
	v_fma_f32 v129, v22, v165, v127
	v_fma_f32 v18, -v19, v161, v58
	v_fma_f32 v22, -v23, v165, v128
	v_fma_f32 v19, v19, v160, v59
	v_fma_f32 v23, v23, v164, v129
	v_mov_b32_e32 v130, v18
	v_mov_b32_e32 v131, v19
	v_mov_b32_e32 v132, v22
	v_mov_b32_e32 v133, v23
	s_nop 1
	v_permlane32_swap_b32_e32 v18, v130
	v_permlane32_swap_b32_e32 v19, v131
	v_permlane32_swap_b32_e32 v22, v132
	v_permlane32_swap_b32_e32 v23, v133
	v_fma_f32 v58, v18, v8, v130
	v_fma_f32 v59, v18, v9, v131
	v_fma_f32 v134, -v19, v9, v58
	v_fma_f32 v135, v19, v8, v59
	v_fma_f32 v128, v22, v10, v132
	v_fma_f32 v129, v22, v11, v133
	v_fma_f32 v136, -v23, v11, v128
	v_fma_f32 v137, v23, v10, v129
	v_cndmask_b32_e64 v134, v134, v136, s[8:9]
	v_cndmask_b32_e64 v135, v135, v137, s[8:9]
	s_lshr_b32 s4, s82, 3
	s_lshl_b32 s4, s4, 15
	s_add_u32 s6, s28, s4
	s_addc_u32 s7, s29, 0
	global_store_dwordx2 v207, v[134:135], s[6:7]
	s_add_i32 s82, s82, 0x100
	s_cmpk_lt_i32 s82, 0x800
	s_cbranch_scc1 .Ls5a_item

.LBB0_320:
	s_or_b64 exec, exec, s[6:7]
	s_add_u32 s12, s74, 0x10ae0000
	s_addc_u32 s13, s75, 0
	v_mov_b32_e32 v69, v174
	s_cmpk_gt_i32 s2, 0x8ff
	s_barrier
	s_cbranch_scc1 .LBB0_364
	v_and_b32_e32 v196, 63, v174
	v_lshrrev_b32_e32 v197, 6, v174
	v_and_b32_e32 v198, 31, v196
	v_lshrrev_b32_e32 v199, 5, v196
	s_and_b32 s80, s2, 7
	v_lshl_add_u32 v200, s80, 3, v197
	v_lshl_add_u32 v201, v200, 6, v198
	v_lshlrev_b32_e32 v202, 6, v201
	v_lshl_add_u32 v202, v199, 5, v202
	global_load_dwordx4 v[24:27], v202, s[24:25] offset:0
	global_load_dwordx4 v[28:31], v202, s[24:25] offset:16
	global_load_dwordx4 v[40:43], v202, s[24:25] offset:2048
	global_load_dwordx4 v[44:47], v202, s[24:25] offset:2064
	global_load_dwordx4 v[32:35], v202, s[26:27] offset:0
	global_load_dwordx4 v[36:39], v202, s[26:27] offset:16
	global_load_dwordx4 v[48:51], v202, s[26:27] offset:2048
	global_load_dwordx4 v[52:55], v202, s[26:27] offset:2064
	v_lshlrev_b32_e32 v203, 3, v201
	s_lshl_b32 s81, s80, 7
	v_lshl_add_u32 v204, v197, 4, s81
	v_lshl_add_u32 v204, v199, 3, v204
	v_lshlrev_b32_e32 v204, 2, v204
	global_load_dwordx4 v[140:143], v204, s[42:43]
	global_load_dwordx4 v[144:147], v204, s[42:43] offset:16
	v_lshl_add_u32 v205, v198, 12, v204
	v_lshlrev_b32_e32 v206, 2, v198
	v_lshl_add_u32 v207, v200, 6, v196
	v_lshlrev_b32_e32 v207, 3, v207
	v_mov_b32_e32 v254, 0x358637bd
	s_mov_b32 s8, 0
	s_mov_b32 s9, -1
	global_load_dwordx2 v[56:57], v203, s[10:11]
	global_load_dwordx2 v[58:59], v203, s[10:11] offset:256
	s_add_u32 s30, s74, 0x12cddc00
	s_addc_u32 s31, s75, 0
	global_load_dwordx2 v[18:19], v207, s[30:31]
	v_and_b32_e32 v172, 15, v196
	v_lshrrev_b32_e32 v173, 4, v196
	v_lshl_add_u32 v60, v200, 4, v172
	v_lshlrev_b32_e32 v202, 8, v60
	v_lshl_add_u32 v202, v173, 3, v202
	s_add_u32 s84, s74, 0x12d65c00
	s_addc_u32 s85, s75, 0
	global_load_dwordx2 v[64:65], v202, s[84:85] offset:0
	global_load_dwordx2 v[66:67], v202, s[84:85] offset:128
	global_load_dwordx2 v[68:69], v202, s[84:85] offset:32
	global_load_dwordx2 v[70:71], v202, s[84:85] offset:160
	global_load_dwordx2 v[72:73], v202, s[84:85] offset:64
	global_load_dwordx2 v[74:75], v202, s[84:85] offset:192
	global_load_dwordx2 v[76:77], v202, s[84:85] offset:96
	global_load_dwordx2 v[78:79], v202, s[84:85] offset:224
	v_lshlrev_b32_e32 v203, 2, v60
	global_load_dword v224, v203, s[58:59]
	v_mov_b32_e32 v177, 0x05040100
	v_mov_b32_e32 v244, 0x07060302
	v_min_u32_e32 v60, 7, v198
	v_lshl_add_u32 v225, v60, 12, v204
	v_lshlrev_b32_e32 v226, 2, v60
	v_mul_u32_u24_e32 v60, 0x2c00, v197
	v_mul_u32_u24_e32 v229, 0x440, v199
	v_lshl_add_u32 v229, v198, 2, v229
	v_add_u32_e32 v229, v229, v60
	v_mul_u32_u24_e32 v230, 0x110, v172
	v_lshl_add_u32 v230, v173, 4, v230
	v_add_u32_e32 v230, v230, v60
	v_lshlrev_b32_e32 v231, 6, v198
	v_lshl_add_u32 v231, v199, 5, v231
	v_add_u32_e32 v245, 0x2200, v60
	v_add_u32_e32 v231, v231, v245
	v_lshlrev_b32_e32 v232, 8, v173
	v_lshl_add_u32 v232, v172, 2, v232
	v_add_u32_e32 v232, v232, v245
	v_lshl_add_u32 v60, v200, 4, v172
	v_lshlrev_b32_e32 v60, 1, v60
	v_lshl_add_u32 v233, v173, 13, v60
	v_add_u32_e32 v241, 0x800, v233
	v_add_u32_e32 v242, 0x1000, v233
	v_add_u32_e32 v243, 0x1800, v233
	s_waitcnt vmcnt(0)
	v_mov_b32_e32 v0, v56
	v_mov_b32_e32 v4, v57
	v_mov_b32_e32 v8, v58
	v_mov_b32_e32 v14, v59
	v_mul_f32_e32 v168, v4, v4
	v_mul_f32_e32 v169, v4, v0
	v_fma_f32 v1, v0, v0, -v168
	v_fma_f32 v5, v0, v4, v169
	v_mul_f32_e32 v170, v14, v14
	v_mul_f32_e32 v171, v14, v8
	v_fma_f32 v9, v8, v8, -v170
	v_fma_f32 v15, v8, v14, v171
	v_mul_f32_e32 v168, v5, v4
	v_mul_f32_e32 v169, v5, v0
	v_fma_f32 v2, v1, v0, -v168
	v_fma_f32 v6, v1, v4, v169
	v_mul_f32_e32 v170, v15, v14
	v_mul_f32_e32 v171, v15, v8
	v_fma_f32 v10, v9, v8, -v170
	v_fma_f32 v16, v9, v14, v171
	v_mul_f32_e32 v168, v5, v5
	v_mul_f32_e32 v169, v5, v1
	v_fma_f32 v3, v1, v1, -v168
	v_fma_f32 v7, v1, v5, v169
	v_mul_f32_e32 v170, v15, v15
	v_mul_f32_e32 v171, v15, v9
	v_fma_f32 v11, v9, v9, -v170
	v_fma_f32 v17, v9, v15, v171
	v_perm_b32 v208, v66, v64, v177
	v_perm_b32 v209, v66, v64, v244
	v_perm_b32 v210, v67, v65, v177
	v_perm_b32 v211, v67, v65, v244
	v_perm_b32 v212, v70, v68, v177
	v_perm_b32 v213, v70, v68, v244
	v_perm_b32 v214, v71, v69, v177
	v_perm_b32 v215, v71, v69, v244
	v_perm_b32 v216, v74, v72, v177
	v_perm_b32 v217, v74, v72, v244
	v_perm_b32 v218, v75, v73, v177
	v_perm_b32 v219, v75, v73, v244
	v_perm_b32 v220, v78, v76, v177
	v_perm_b32 v221, v78, v76, v244
	v_perm_b32 v222, v79, v77, v177
	v_perm_b32 v223, v79, v77, v244
	v_mov_b32_e32 v22, 0
	v_mov_b32_e32 v23, 0
	s_mov_b32 s98, -1
	s_mov_b32 s99, 0
	s_mov_b32 s82, s2
	s_lshr_b32 s4, s82, 10
	s_bfe_u32 s6, s82, 0x70003
	s_lshl_b32 s4, s4, 13
	s_lshl_b32 s6, s6, 6
	s_add_i32 s31, s4, s6
	s_lshl_b32 s6, s31, 12
	s_add_u32 s84, s38, s6
	s_addc_u32 s85, s39, 0
	s_add_u32 s88, s84, 0x20000
	s_addc_u32 s89, s85, 0
	s_lshl_b32 s6, s31, 2
	s_add_u32 s86, s22, s6
	s_addc_u32 s87, s23, 0
	global_load_dwordx4 v[178:181], v205, s[84:85]
	global_load_dwordx4 v[182:185], v205, s[84:85] offset:16
	global_load_dword v194, v206, s[86:87]
	global_load_dwordx4 v[186:189], v205, s[88:89]
	global_load_dwordx4 v[190:193], v205, s[88:89] offset:16
	global_load_dword v195, v206, s[86:87] offset:128
	s_lshr_b32 s65, s2, 10
	s_bfe_u32 s66, s2, 0x70003
	s_mov_b32 s67, 0
	s_lshl_b32 s4, s65, 22
	s_add_u32 s100, s28, s4
	s_addc_u32 s101, s29, 0
	s_add_i32 s57, s66, -1
	s_max_i32 s57, s57, 0
	s_add_i32 s4, s67, 0
	s_min_i32 s4, s4, s57
	s_lshl_b32 s4, s4, 15
	s_add_u32 s6, s100, s4
	s_addc_u32 s7, s101, 0
	global_load_dwordx2 v[64:65], v207, s[6:7]
	s_add_i32 s4, s67, 1
	s_min_i32 s4, s4, s57
	s_lshl_b32 s4, s4, 15
	s_add_u32 s6, s100, s4
	s_addc_u32 s7, s101, 0
	global_load_dwordx2 v[66:67], v207, s[6:7]
	s_add_i32 s4, s67, 2
	s_min_i32 s4, s4, s57
	s_lshl_b32 s4, s4, 15
	s_add_u32 s6, s100, s4
	s_addc_u32 s7, s101, 0
	global_load_dwordx2 v[68:69], v207, s[6:7]
	s_add_i32 s4, s67, 3
	s_min_i32 s4, s4, s57
	s_lshl_b32 s4, s4, 15
	s_add_u32 s6, s100, s4
	s_addc_u32 s7, s101, 0
	global_load_dwordx2 v[70:71], v207, s[6:7]
	s_add_i32 s4, s67, 4
	s_min_i32 s4, s4, s57
	s_lshl_b32 s4, s4, 15
	s_add_u32 s6, s100, s4
	s_addc_u32 s7, s101, 0
	global_load_dwordx2 v[72:73], v207, s[6:7]
	s_add_i32 s4, s67, 5
	s_min_i32 s4, s4, s57
	s_lshl_b32 s4, s4, 15
	s_add_u32 s6, s100, s4
	s_addc_u32 s7, s101, 0
	global_load_dwordx2 v[74:75], v207, s[6:7]
	s_add_i32 s4, s67, 6
	s_min_i32 s4, s4, s57
	s_lshl_b32 s4, s4, 15
	s_add_u32 s6, s100, s4
	s_addc_u32 s7, s101, 0
	global_load_dwordx2 v[76:77], v207, s[6:7]
	s_add_i32 s4, s67, 7
	s_min_i32 s4, s4, s57
	s_lshl_b32 s4, s4, 15
	s_add_u32 s6, s100, s4
	s_addc_u32 s7, s101, 0
	global_load_dwordx2 v[78:79], v207, s[6:7]
	s_add_i32 s4, s67, 8
	s_min_i32 s4, s4, s57
	s_lshl_b32 s4, s4, 15
	s_add_u32 s6, s100, s4
	s_addc_u32 s7, s101, 0
	global_load_dwordx2 v[80:81], v207, s[6:7]
	s_add_i32 s4, s67, 9
	s_min_i32 s4, s4, s57
	s_lshl_b32 s4, s4, 15
	s_add_u32 s6, s100, s4
	s_addc_u32 s7, s101, 0
	global_load_dwordx2 v[82:83], v207, s[6:7]
	s_add_i32 s4, s67, 10
	s_min_i32 s4, s4, s57
	s_lshl_b32 s4, s4, 15
	s_add_u32 s6, s100, s4
	s_addc_u32 s7, s101, 0
	global_load_dwordx2 v[84:85], v207, s[6:7]
	s_add_i32 s4, s67, 11
	s_min_i32 s4, s4, s57
	s_lshl_b32 s4, s4, 15
	s_add_u32 s6, s100, s4
	s_addc_u32 s7, s101, 0
	global_load_dwordx2 v[86:87], v207, s[6:7]
	s_add_i32 s4, s67, 12
	s_min_i32 s4, s4, s57
	s_lshl_b32 s4, s4, 15
	s_add_u32 s6, s100, s4
	s_addc_u32 s7, s101, 0
	global_load_dwordx2 v[88:89], v207, s[6:7]
	s_add_i32 s4, s67, 13
	s_min_i32 s4, s4, s57
	s_lshl_b32 s4, s4, 15
	s_add_u32 s6, s100, s4
	s_addc_u32 s7, s101, 0
	global_load_dwordx2 v[90:91], v207, s[6:7]
	s_add_i32 s4, s67, 14
	s_min_i32 s4, s4, s57
	s_lshl_b32 s4, s4, 15
	s_add_u32 s6, s100, s4
	s_addc_u32 s7, s101, 0
	global_load_dwordx2 v[92:93], v207, s[6:7]
	s_add_i32 s4, s67, 15
	s_min_i32 s4, s4, s57
	s_lshl_b32 s4, s4, 15
	s_add_u32 s6, s100, s4
	s_addc_u32 s7, s101, 0
	global_load_dwordx2 v[94:95], v207, s[6:7]
	s_add_i32 s4, s67, 16
	s_min_i32 s4, s4, s57
	s_lshl_b32 s4, s4, 15
	s_add_u32 s6, s100, s4
	s_addc_u32 s7, s101, 0
	global_load_dwordx2 v[96:97], v207, s[6:7]
	s_add_i32 s4, s67, 17
	s_min_i32 s4, s4, s57
	s_lshl_b32 s4, s4, 15
	s_add_u32 s6, s100, s4
	s_addc_u32 s7, s101, 0
	global_load_dwordx2 v[98:99], v207, s[6:7]
	s_add_i32 s4, s67, 18
	s_min_i32 s4, s4, s57
	s_lshl_b32 s4, s4, 15
	s_add_u32 s6, s100, s4
	s_addc_u32 s7, s101, 0
	global_load_dwordx2 v[100:101], v207, s[6:7]
	s_add_i32 s4, s67, 19
	s_min_i32 s4, s4, s57
	s_lshl_b32 s4, s4, 15
	s_add_u32 s6, s100, s4
	s_addc_u32 s7, s101, 0
	global_load_dwordx2 v[102:103], v207, s[6:7]
	s_add_i32 s4, s67, 20
	s_min_i32 s4, s4, s57
	s_lshl_b32 s4, s4, 15
	s_add_u32 s6, s100, s4
	s_addc_u32 s7, s101, 0
	global_load_dwordx2 v[104:105], v207, s[6:7]
	s_add_i32 s4, s67, 21
	s_min_i32 s4, s4, s57
	s_lshl_b32 s4, s4, 15
	s_add_u32 s6, s100, s4
	s_addc_u32 s7, s101, 0
	global_load_dwordx2 v[106:107], v207, s[6:7]
	s_add_i32 s4, s67, 22
	s_min_i32 s4, s4, s57
	s_lshl_b32 s4, s4, 15
	s_add_u32 s6, s100, s4
	s_addc_u32 s7, s101, 0
	global_load_dwordx2 v[108:109], v207, s[6:7]
	s_add_i32 s4, s67, 23
	s_min_i32 s4, s4, s57
	s_lshl_b32 s4, s4, 15
	s_add_u32 s6, s100, s4
	s_addc_u32 s7, s101, 0
	global_load_dwordx2 v[110:111], v207, s[6:7]
	s_add_i32 s4, s67, 24
	s_min_i32 s4, s4, s57
	s_lshl_b32 s4, s4, 15
	s_add_u32 s6, s100, s4
	s_addc_u32 s7, s101, 0
	global_load_dwordx2 v[112:113], v207, s[6:7]
	s_add_i32 s4, s67, 25
	s_min_i32 s4, s4, s57
	s_lshl_b32 s4, s4, 15
	s_add_u32 s6, s100, s4
	s_addc_u32 s7, s101, 0
	global_load_dwordx2 v[114:115], v207, s[6:7]
	s_add_i32 s4, s67, 26
	s_min_i32 s4, s4, s57
	s_lshl_b32 s4, s4, 15
	s_add_u32 s6, s100, s4
	s_addc_u32 s7, s101, 0
	global_load_dwordx2 v[116:117], v207, s[6:7]
	s_add_i32 s4, s67, 27
	s_min_i32 s4, s4, s57
	s_lshl_b32 s4, s4, 15
	s_add_u32 s6, s100, s4
	s_addc_u32 s7, s101, 0
	global_load_dwordx2 v[118:119], v207, s[6:7]
	s_add_i32 s4, s67, 28
	s_min_i32 s4, s4, s57
	s_lshl_b32 s4, s4, 15
	s_add_u32 s6, s100, s4
	s_addc_u32 s7, s101, 0
	global_load_dwordx2 v[120:121], v207, s[6:7]
	s_add_i32 s4, s67, 29
	s_min_i32 s4, s4, s57
	s_lshl_b32 s4, s4, 15
	s_add_u32 s6, s100, s4
	s_addc_u32 s7, s101, 0
	global_load_dwordx2 v[122:123], v207, s[6:7]
	s_add_i32 s4, s67, 30
	s_min_i32 s4, s4, s57
	s_lshl_b32 s4, s4, 15
	s_add_u32 s6, s100, s4
	s_addc_u32 s7, s101, 0
	global_load_dwordx2 v[124:125], v207, s[6:7]
	s_add_i32 s4, s67, 31
	s_min_i32 s4, s4, s57
	s_lshl_b32 s4, s4, 15
	s_add_u32 s6, s100, s4
	s_addc_u32 s7, s101, 0
	global_load_dwordx2 v[126:127], v207, s[6:7]

.Ls5b_car_ok:
	s_sub_i32 s57, s52, s99
	s_waitcnt vmcnt(0)
	s_cmp_le_i32 s57, 0
	s_cbranch_scc1 .Ls5b_car_done
	v_fma_f32 v168, v22, v18, v64
	v_fma_f32 v169, v22, v19, v65
	v_fma_f32 v22, -v23, v19, v168
	v_fma_f32 v23, v23, v18, v169
	s_cmp_le_i32 s57, 1
	s_cbranch_scc1 .Ls5b_car_done
	v_fma_f32 v168, v22, v18, v66
	v_fma_f32 v169, v22, v19, v67
	v_fma_f32 v22, -v23, v19, v168
	v_fma_f32 v23, v23, v18, v169
	s_cmp_le_i32 s57, 2
	s_cbranch_scc1 .Ls5b_car_done
	v_fma_f32 v168, v22, v18, v68
	v_fma_f32 v169, v22, v19, v69
	v_fma_f32 v22, -v23, v19, v168
	v_fma_f32 v23, v23, v18, v169
	s_cmp_le_i32 s57, 3
	s_cbranch_scc1 .Ls5b_car_done
	v_fma_f32 v168, v22, v18, v70
	v_fma_f32 v169, v22, v19, v71
	v_fma_f32 v22, -v23, v19, v168
	v_fma_f32 v23, v23, v18, v169
	s_cmp_le_i32 s57, 4
	s_cbranch_scc1 .Ls5b_car_done
	v_fma_f32 v168, v22, v18, v72
	v_fma_f32 v169, v22, v19, v73
	v_fma_f32 v22, -v23, v19, v168
	v_fma_f32 v23, v23, v18, v169
	s_cmp_le_i32 s57, 5
	s_cbranch_scc1 .Ls5b_car_done
	v_fma_f32 v168, v22, v18, v74
	v_fma_f32 v169, v22, v19, v75
	v_fma_f32 v22, -v23, v19, v168
	v_fma_f32 v23, v23, v18, v169
	s_cmp_le_i32 s57, 6
	s_cbranch_scc1 .Ls5b_car_done
	v_fma_f32 v168, v22, v18, v76
	v_fma_f32 v169, v22, v19, v77
	v_fma_f32 v22, -v23, v19, v168
	v_fma_f32 v23, v23, v18, v169
	s_cmp_le_i32 s57, 7
	s_cbranch_scc1 .Ls5b_car_done
	v_fma_f32 v168, v22, v18, v78
	v_fma_f32 v169, v22, v19, v79
	v_fma_f32 v22, -v23, v19, v168
	v_fma_f32 v23, v23, v18, v169
	s_cmp_le_i32 s57, 8
	s_cbranch_scc1 .Ls5b_car_done
	v_fma_f32 v168, v22, v18, v80
	v_fma_f32 v169, v22, v19, v81
	v_fma_f32 v22, -v23, v19, v168
	v_fma_f32 v23, v23, v18, v169
	s_cmp_le_i32 s57, 9
	s_cbranch_scc1 .Ls5b_car_done
	v_fma_f32 v168, v22, v18, v82
	v_fma_f32 v169, v22, v19, v83
	v_fma_f32 v22, -v23, v19, v168
	v_fma_f32 v23, v23, v18, v169
	s_cmp_le_i32 s57, 10
	s_cbranch_scc1 .Ls5b_car_done
	v_fma_f32 v168, v22, v18, v84
	v_fma_f32 v169, v22, v19, v85
	v_fma_f32 v22, -v23, v19, v168
	v_fma_f32 v23, v23, v18, v169
	s_cmp_le_i32 s57, 11
	s_cbranch_scc1 .Ls5b_car_done
	v_fma_f32 v168, v22, v18, v86
	v_fma_f32 v169, v22, v19, v87
	v_fma_f32 v22, -v23, v19, v168
	v_fma_f32 v23, v23, v18, v169
	s_cmp_le_i32 s57, 12
	s_cbranch_scc1 .Ls5b_car_done
	v_fma_f32 v168, v22, v18, v88
	v_fma_f32 v169, v22, v19, v89
	v_fma_f32 v22, -v23, v19, v168
	v_fma_f32 v23, v23, v18, v169
	s_cmp_le_i32 s57, 13
	s_cbranch_scc1 .Ls5b_car_done
	v_fma_f32 v168, v22, v18, v90
	v_fma_f32 v169, v22, v19, v91
	v_fma_f32 v22, -v23, v19, v168
	v_fma_f32 v23, v23, v18, v169
	s_cmp_le_i32 s57, 14
	s_cbranch_scc1 .Ls5b_car_done
	v_fma_f32 v168, v22, v18, v92
	v_fma_f32 v169, v22, v19, v93
	v_fma_f32 v22, -v23, v19, v168
	v_fma_f32 v23, v23, v18, v169
	s_cmp_le_i32 s57, 15
	s_cbranch_scc1 .Ls5b_car_done
	v_fma_f32 v168, v22, v18, v94
	v_fma_f32 v169, v22, v19, v95
	v_fma_f32 v22, -v23, v19, v168
	v_fma_f32 v23, v23, v18, v169
	s_cmp_le_i32 s57, 16
	s_cbranch_scc1 .Ls5b_car_done
	v_fma_f32 v168, v22, v18, v96
	v_fma_f32 v169, v22, v19, v97
	v_fma_f32 v22, -v23, v19, v168
	v_fma_f32 v23, v23, v18, v169
	s_cmp_le_i32 s57, 17
	s_cbranch_scc1 .Ls5b_car_done
	v_fma_f32 v168, v22, v18, v98
	v_fma_f32 v169, v22, v19, v99
	v_fma_f32 v22, -v23, v19, v168
	v_fma_f32 v23, v23, v18, v169
	s_cmp_le_i32 s57, 18
	s_cbranch_scc1 .Ls5b_car_done
	v_fma_f32 v168, v22, v18, v100
	v_fma_f32 v169, v22, v19, v101
	v_fma_f32 v22, -v23, v19, v168
	v_fma_f32 v23, v23, v18, v169
	s_cmp_le_i32 s57, 19
	s_cbranch_scc1 .Ls5b_car_done
	v_fma_f32 v168, v22, v18, v102
	v_fma_f32 v169, v22, v19, v103
	v_fma_f32 v22, -v23, v19, v168
	v_fma_f32 v23, v23, v18, v169
	s_cmp_le_i32 s57, 20
	s_cbranch_scc1 .Ls5b_car_done
	v_fma_f32 v168, v22, v18, v104
	v_fma_f32 v169, v22, v19, v105
	v_fma_f32 v22, -v23, v19, v168
	v_fma_f32 v23, v23, v18, v169
	s_cmp_le_i32 s57, 21
	s_cbranch_scc1 .Ls5b_car_done
	v_fma_f32 v168, v22, v18, v106
	v_fma_f32 v169, v22, v19, v107
	v_fma_f32 v22, -v23, v19, v168
	v_fma_f32 v23, v23, v18, v169
	s_cmp_le_i32 s57, 22
	s_cbranch_scc1 .Ls5b_car_done
	v_fma_f32 v168, v22, v18, v108
	v_fma_f32 v169, v22, v19, v109
	v_fma_f32 v22, -v23, v19, v168
	v_fma_f32 v23, v23, v18, v169
	s_cmp_le_i32 s57, 23
	s_cbranch_scc1 .Ls5b_car_done
	v_fma_f32 v168, v22, v18, v110
	v_fma_f32 v169, v22, v19, v111
	v_fma_f32 v22, -v23, v19, v168
	v_fma_f32 v23, v23, v18, v169
	s_cmp_le_i32 s57, 24
	s_cbranch_scc1 .Ls5b_car_done
	v_fma_f32 v168, v22, v18, v112
	v_fma_f32 v169, v22, v19, v113
	v_fma_f32 v22, -v23, v19, v168
	v_fma_f32 v23, v23, v18, v169
	s_cmp_le_i32 s57, 25
	s_cbranch_scc1 .Ls5b_car_done
	v_fma_f32 v168, v22, v18, v114
	v_fma_f32 v169, v22, v19, v115
	v_fma_f32 v22, -v23, v19, v168
	v_fma_f32 v23, v23, v18, v169
	s_cmp_le_i32 s57, 26
	s_cbranch_scc1 .Ls5b_car_done
	v_fma_f32 v168, v22, v18, v116
	v_fma_f32 v169, v22, v19, v117
	v_fma_f32 v22, -v23, v19, v168
	v_fma_f32 v23, v23, v18, v169
	s_cmp_le_i32 s57, 27
	s_cbranch_scc1 .Ls5b_car_done
	v_fma_f32 v168, v22, v18, v118
	v_fma_f32 v169, v22, v19, v119
	v_fma_f32 v22, -v23, v19, v168
	v_fma_f32 v23, v23, v18, v169
	s_cmp_le_i32 s57, 28
	s_cbranch_scc1 .Ls5b_car_done
	v_fma_f32 v168, v22, v18, v120
	v_fma_f32 v169, v22, v19, v121
	v_fma_f32 v22, -v23, v19, v168
	v_fma_f32 v23, v23, v18, v169
	s_cmp_le_i32 s57, 29
	s_cbranch_scc1 .Ls5b_car_done
	v_fma_f32 v168, v22, v18, v122
	v_fma_f32 v169, v22, v19, v123
	v_fma_f32 v22, -v23, v19, v168
	v_fma_f32 v23, v23, v18, v169
	s_cmp_le_i32 s57, 30
	s_cbranch_scc1 .Ls5b_car_done
	v_fma_f32 v168, v22, v18, v124
	v_fma_f32 v169, v22, v19, v125
	v_fma_f32 v22, -v23, v19, v168
	v_fma_f32 v23, v23, v18, v169
	s_cmp_le_i32 s57, 31
	s_cbranch_scc1 .Ls5b_car_done
	v_fma_f32 v168, v22, v18, v126
	v_fma_f32 v169, v22, v19, v127
	v_fma_f32 v22, -v23, v19, v168
	v_fma_f32 v23, v23, v18, v169

.Ls5b_cin_done:
	s_nop 1
	v_permlane32_swap_b32_e32 v128, v130
	v_permlane32_swap_b32_e32 v129, v131
	s_waitcnt vmcnt(0)
	s_add_i32 s4, s31, 0
	s_lshl_b32 s4, s4, 11
	s_add_u32 s86, s12, s4
	s_addc_u32 s87, s13, 0
	s_add_u32 s88, s86, 0x8000
	s_addc_u32 s89, s87, 0
	v_fmamk_f32 v56, v194, 0x3a800000, v254
	v_rsq_f32_e32 v56, v56
	s_nop 0
	v_pk_mul_f32 v[148:149], v[178:179], v[56:57] op_sel_hi:[1,0]
	v_pk_mul_f32 v[150:151], v[180:181], v[56:57] op_sel_hi:[1,0]
	v_pk_mul_f32 v[152:153], v[182:183], v[56:57] op_sel_hi:[1,0]
	v_pk_mul_f32 v[154:155], v[184:185], v[56:57] op_sel_hi:[1,0]
	v_pk_mul_f32 v[148:149], v[140:141], v[148:149]
	v_pk_mul_f32 v[150:151], v[142:143], v[150:151]
	v_pk_mul_f32 v[152:153], v[144:145], v[152:153]
	v_pk_mul_f32 v[154:155], v[146:147], v[154:155]
	global_load_dwordx4 v[178:181], v227, s[90:91]
	global_load_dwordx4 v[182:185], v227, s[90:91] offset:16
	global_load_dword v194, v228, s[92:93]
	ds_write_b128 v231, v[148:151] offset:0
	ds_write_b128 v231, v[152:155] offset:16
	s_nop 1
	v_mfma_f32_32x32x2_f32 v[64:79], v148, v24, 0
	v_mfma_f32_32x32x2_f32 v[80:95], v148, v32, 0
	v_mfma_f32_32x32x2_f32 v[96:111], v148, v40, 0
	v_mfma_f32_32x32x2_f32 v[112:127], v148, v48, 0
	v_mfma_f32_32x32x2_f32 v[64:79], v149, v25, v[64:79]
	v_mfma_f32_32x32x2_f32 v[80:95], v149, v33, v[80:95]
	v_mfma_f32_32x32x2_f32 v[96:111], v149, v41, v[96:111]
	v_mfma_f32_32x32x2_f32 v[112:127], v149, v49, v[112:127]
	v_mfma_f32_32x32x2_f32 v[64:79], v150, v26, v[64:79]
	v_mfma_f32_32x32x2_f32 v[80:95], v150, v34, v[80:95]
	v_mfma_f32_32x32x2_f32 v[96:111], v150, v42, v[96:111]
	v_mfma_f32_32x32x2_f32 v[112:127], v150, v50, v[112:127]
	v_mfma_f32_32x32x2_f32 v[64:79], v151, v27, v[64:79]
	v_mfma_f32_32x32x2_f32 v[80:95], v151, v35, v[80:95]
	v_mfma_f32_32x32x2_f32 v[96:111], v151, v43, v[96:111]
	v_mfma_f32_32x32x2_f32 v[112:127], v151, v51, v[112:127]
	v_mfma_f32_32x32x2_f32 v[64:79], v152, v28, v[64:79]
	v_mfma_f32_32x32x2_f32 v[80:95], v152, v36, v[80:95]
	v_mfma_f32_32x32x2_f32 v[96:111], v152, v44, v[96:111]
	v_mfma_f32_32x32x2_f32 v[112:127], v152, v52, v[112:127]
	v_mfma_f32_32x32x2_f32 v[64:79], v153, v29, v[64:79]
	v_mfma_f32_32x32x2_f32 v[80:95], v153, v37, v[80:95]
	v_mfma_f32_32x32x2_f32 v[96:111], v153, v45, v[96:111]
	v_mfma_f32_32x32x2_f32 v[112:127], v153, v53, v[112:127]
	v_mfma_f32_32x32x2_f32 v[64:79], v154, v30, v[64:79]
	v_mfma_f32_32x32x2_f32 v[80:95], v154, v38, v[80:95]
	v_mfma_f32_32x32x2_f32 v[96:111], v154, v46, v[96:111]
	v_mfma_f32_32x32x2_f32 v[112:127], v154, v54, v[112:127]
	v_mfma_f32_32x32x2_f32 v[64:79], v155, v31, v[64:79]
	v_mfma_f32_32x32x2_f32 v[80:95], v155, v39, v[80:95]
	v_mfma_f32_32x32x2_f32 v[96:111], v155, v47, v[96:111]
	v_mfma_f32_32x32x2_f32 v[112:127], v155, v55, v[112:127]
	s_nop 7
	s_nop 7
	s_nop 1
	v_fmac_f32_e32 v65, v64, v0
	v_fmac_f32_e32 v97, v96, v8
	v_fmac_f32_e32 v69, v68, v0
	v_fmac_f32_e32 v101, v100, v8
	v_fmac_f32_e32 v73, v72, v0
	v_fmac_f32_e32 v105, v104, v8
	v_fmac_f32_e32 v77, v76, v0
	v_fmac_f32_e32 v109, v108, v8
	v_fmac_f32_e32 v81, v64, v4
	v_fmac_f32_e32 v113, v96, v14
	v_fmac_f32_e32 v85, v68, v4
	v_fmac_f32_e32 v117, v100, v14
	v_fmac_f32_e32 v89, v72, v4
	v_fmac_f32_e32 v121, v104, v14
	v_fmac_f32_e32 v93, v76, v4
	v_fmac_f32_e32 v125, v108, v14
	v_fma_f32 v65, -v80, v4, v65
	v_fma_f32 v97, -v112, v14, v97
	v_fma_f32 v69, -v84, v4, v69
	v_fma_f32 v101, -v116, v14, v101
	v_fma_f32 v73, -v88, v4, v73
	v_fma_f32 v105, -v120, v14, v105
	v_fma_f32 v77, -v92, v4, v77
	v_fma_f32 v109, -v124, v14, v109
	v_fmac_f32_e32 v81, v80, v0
	v_fmac_f32_e32 v113, v112, v8
	v_fmac_f32_e32 v85, v84, v0
	v_fmac_f32_e32 v117, v116, v8
	v_fmac_f32_e32 v89, v88, v0
	v_fmac_f32_e32 v121, v120, v8
	v_fmac_f32_e32 v93, v92, v0
	v_fmac_f32_e32 v125, v124, v8
	v_fmac_f32_e32 v66, v65, v0
	v_fmac_f32_e32 v98, v97, v8
	v_fmac_f32_e32 v70, v69, v0
	v_fmac_f32_e32 v102, v101, v8
	v_fmac_f32_e32 v74, v73, v0
	v_fmac_f32_e32 v106, v105, v8
	v_fmac_f32_e32 v78, v77, v0
	v_fmac_f32_e32 v110, v109, v8
	v_fmac_f32_e32 v82, v65, v4
	v_fmac_f32_e32 v114, v97, v14
	v_fmac_f32_e32 v86, v69, v4
	v_fmac_f32_e32 v118, v101, v14
	v_fmac_f32_e32 v90, v73, v4
	v_fmac_f32_e32 v122, v105, v14
	v_fmac_f32_e32 v94, v77, v4
	v_fmac_f32_e32 v126, v109, v14
	v_fma_f32 v66, -v81, v4, v66
	v_fma_f32 v98, -v113, v14, v98
	v_fma_f32 v70, -v85, v4, v70
	v_fma_f32 v102, -v117, v14, v102
	v_fma_f32 v74, -v89, v4, v74
	v_fma_f32 v106, -v121, v14, v106
	v_fma_f32 v78, -v93, v4, v78
	v_fma_f32 v110, -v125, v14, v110
	v_fmac_f32_e32 v82, v81, v0
	v_fmac_f32_e32 v114, v113, v8
	v_fmac_f32_e32 v86, v85, v0
	v_fmac_f32_e32 v118, v117, v8
	v_fmac_f32_e32 v90, v89, v0
	v_fmac_f32_e32 v122, v121, v8
	v_fmac_f32_e32 v94, v93, v0
	v_fmac_f32_e32 v126, v125, v8
	v_fmac_f32_e32 v67, v66, v0
	v_fmac_f32_e32 v99, v98, v8
	v_fmac_f32_e32 v71, v70, v0
	v_fmac_f32_e32 v103, v102, v8
	v_fmac_f32_e32 v75, v74, v0
	v_fmac_f32_e32 v107, v106, v8
	v_fmac_f32_e32 v79, v78, v0
	v_fmac_f32_e32 v111, v110, v8
	v_fmac_f32_e32 v83, v66, v4
	v_fmac_f32_e32 v115, v98, v14
	v_fmac_f32_e32 v87, v70, v4
	v_fmac_f32_e32 v119, v102, v14
	v_fmac_f32_e32 v91, v74, v4
	v_fmac_f32_e32 v123, v106, v14
	v_fmac_f32_e32 v95, v78, v4
	v_fmac_f32_e32 v127, v110, v14
	v_fma_f32 v67, -v82, v4, v67
	v_fma_f32 v99, -v114, v14, v99
	v_fma_f32 v71, -v86, v4, v71
	v_fma_f32 v103, -v118, v14, v103
	v_fma_f32 v75, -v90, v4, v75
	v_fma_f32 v107, -v122, v14, v107
	v_fma_f32 v79, -v94, v4, v79
	v_fma_f32 v111, -v126, v14, v111
	v_fmac_f32_e32 v83, v82, v0
	v_fmac_f32_e32 v115, v114, v8
	v_fmac_f32_e32 v87, v86, v0
	v_fmac_f32_e32 v119, v118, v8
	v_fmac_f32_e32 v91, v90, v0
	v_fmac_f32_e32 v123, v122, v8
	v_fmac_f32_e32 v95, v94, v0
	v_fmac_f32_e32 v127, v126, v8
	v_mov_b32_e32 v158, v67
	v_mov_b32_e32 v160, v67
	v_mov_b32_e32 v159, v83
	v_mov_b32_e32 v161, v83
	v_mov_b32_e32 v164, v99
	v_mov_b32_e32 v166, v99
	v_mov_b32_e32 v165, v115
	v_mov_b32_e32 v167, v115
	s_nop 1
	v_permlane32_swap_b32_e32 v158, v160
	v_permlane32_swap_b32_e32 v159, v161
	v_permlane32_swap_b32_e32 v164, v166
	v_permlane32_swap_b32_e32 v165, v167
	v_fma_f32 v168, v128, v3, v158
	v_fma_f32 v170, v130, v11, v164
	v_fma_f32 v169, v128, v7, v159
	v_fma_f32 v171, v130, v17, v165
	v_fma_f32 v132, -v129, v7, v168
	v_fma_f32 v134, -v131, v17, v170
	v_fma_f32 v133, v129, v3, v169
	v_fma_f32 v135, v131, v11, v171
	v_cndmask_b32_e64 v136, v128, v132, s[8:9]
	v_cndmask_b32_e64 v137, v129, v133, s[8:9]
	v_cndmask_b32_e64 v156, v130, v134, s[8:9]
	v_cndmask_b32_e64 v157, v131, v135, s[8:9]
	v_fma_f32 v168, v132, v3, v160
	v_fma_f32 v170, v134, v11, v166
	v_fma_f32 v169, v132, v7, v161
	v_fma_f32 v171, v134, v17, v167
	v_fma_f32 v128, -v133, v7, v168
	v_fma_f32 v130, -v135, v17, v170
	v_fma_f32 v129, v133, v3, v169
	v_fma_f32 v131, v135, v11, v171
	v_mov_b32_e32 v246, v128
	v_mov_b32_e32 v247, v129
	v_mov_b32_e32 v248, v130
	v_mov_b32_e32 v249, v131
	v_pk_fma_f32 v[64:65], v[0:1], v[136:137], v[64:65] op_sel_hi:[1,0,1]
	v_mov_b32_e32 v158, v71
	v_pk_fma_f32 v[80:81], v[0:1], v[136:137], v[80:81] op_sel:[0,1,0]
	v_mov_b32_e32 v160, v71
	v_pk_fma_f32 v[66:67], v[2:3], v[136:137], v[66:67] op_sel_hi:[1,0,1]
	v_mov_b32_e32 v159, v87
	v_pk_fma_f32 v[82:83], v[2:3], v[136:137], v[82:83] op_sel:[0,1,0]
	v_mov_b32_e32 v161, v87
	v_pk_fma_f32 v[96:97], v[8:9], v[156:157], v[96:97] op_sel_hi:[1,0,1]
	v_mov_b32_e32 v164, v103
	v_pk_fma_f32 v[112:113], v[8:9], v[156:157], v[112:113] op_sel:[0,1,0]
	v_mov_b32_e32 v166, v103
	v_pk_fma_f32 v[98:99], v[10:11], v[156:157], v[98:99] op_sel_hi:[1,0,1]
	v_mov_b32_e32 v165, v119
	v_pk_fma_f32 v[114:115], v[10:11], v[156:157], v[114:115] op_sel:[0,1,0]
	v_mov_b32_e32 v167, v119
	v_pk_fma_f32 v[64:65], v[4:5], v[136:137], v[64:65] op_sel:[0,1,0] neg_lo:[1,0,0] neg_hi:[1,0,0]
	s_nop 1
	v_pk_fma_f32 v[80:81], v[4:5], v[136:137], v[80:81] op_sel_hi:[1,0,1]
	v_permlane32_swap_b32_e32 v158, v160
	v_pk_fma_f32 v[66:67], v[6:7], v[136:137], v[66:67] op_sel:[0,1,0] neg_lo:[1,0,0] neg_hi:[1,0,0]
	v_permlane32_swap_b32_e32 v159, v161
	v_pk_fma_f32 v[82:83], v[6:7], v[136:137], v[82:83] op_sel_hi:[1,0,1]
	v_permlane32_swap_b32_e32 v164, v166
	v_pk_fma_f32 v[96:97], v[14:15], v[156:157], v[96:97] op_sel:[0,1,0] neg_lo:[1,0,0] neg_hi:[1,0,0]
	v_permlane32_swap_b32_e32 v165, v167
	v_pk_fma_f32 v[112:113], v[14:15], v[156:157], v[112:113] op_sel_hi:[1,0,1]
	v_fma_f32 v168, v128, v3, v158
	v_pk_fma_f32 v[98:99], v[16:17], v[156:157], v[98:99] op_sel:[0,1,0] neg_lo:[1,0,0] neg_hi:[1,0,0]
	v_fma_f32 v170, v130, v11, v164
	v_pk_fma_f32 v[114:115], v[16:17], v[156:157], v[114:115] op_sel_hi:[1,0,1]
	v_fma_f32 v169, v128, v7, v159
	v_fma_f32 v171, v130, v17, v165
	v_fma_f32 v132, -v129, v7, v168
	v_fma_f32 v134, -v131, v17, v170
	v_fma_f32 v133, v129, v3, v169
	v_fma_f32 v135, v131, v11, v171
	v_cndmask_b32_e64 v172, v128, v132, s[8:9]
	v_cndmask_b32_e64 v173, v129, v133, s[8:9]
	v_cndmask_b32_e64 v244, v130, v134, s[8:9]
	v_cndmask_b32_e64 v245, v131, v135, s[8:9]
	v_fma_f32 v168, v132, v3, v160
	v_fma_f32 v170, v134, v11, v166
	v_fma_f32 v169, v132, v7, v161
	v_fma_f32 v171, v134, v17, v167
	v_fma_f32 v128, -v133, v7, v168
	v_fma_f32 v130, -v135, v17, v170
	v_fma_f32 v129, v133, v3, v169
	v_fma_f32 v131, v135, v11, v171
	v_pk_fma_f32 v[68:69], v[0:1], v[172:173], v[68:69] op_sel_hi:[1,0,1]
	v_mov_b32_e32 v158, v75
	v_pk_fma_f32 v[84:85], v[0:1], v[172:173], v[84:85] op_sel:[0,1,0]
	v_mov_b32_e32 v160, v75
	v_pk_fma_f32 v[70:71], v[2:3], v[172:173], v[70:71] op_sel_hi:[1,0,1]
	v_mov_b32_e32 v159, v91
	v_pk_fma_f32 v[86:87], v[2:3], v[172:173], v[86:87] op_sel:[0,1,0]
	v_mov_b32_e32 v161, v91
	v_pk_fma_f32 v[100:101], v[8:9], v[244:245], v[100:101] op_sel_hi:[1,0,1]
	v_mov_b32_e32 v164, v107
	v_pk_fma_f32 v[116:117], v[8:9], v[244:245], v[116:117] op_sel:[0,1,0]
	v_mov_b32_e32 v166, v107
	v_pk_fma_f32 v[102:103], v[10:11], v[244:245], v[102:103] op_sel_hi:[1,0,1]
	v_mov_b32_e32 v165, v123
	v_pk_fma_f32 v[118:119], v[10:11], v[244:245], v[118:119] op_sel:[0,1,0]
	v_mov_b32_e32 v167, v123
	v_pk_fma_f32 v[68:69], v[4:5], v[172:173], v[68:69] op_sel:[0,1,0] neg_lo:[1,0,0] neg_hi:[1,0,0]
	s_nop 1
	v_pk_fma_f32 v[84:85], v[4:5], v[172:173], v[84:85] op_sel_hi:[1,0,1]
	v_permlane32_swap_b32_e32 v158, v160
	v_pk_fma_f32 v[70:71], v[6:7], v[172:173], v[70:71] op_sel:[0,1,0] neg_lo:[1,0,0] neg_hi:[1,0,0]
	v_permlane32_swap_b32_e32 v159, v161
	v_pk_fma_f32 v[86:87], v[6:7], v[172:173], v[86:87] op_sel_hi:[1,0,1]
	v_permlane32_swap_b32_e32 v164, v166
	v_pk_fma_f32 v[100:101], v[14:15], v[244:245], v[100:101] op_sel:[0,1,0] neg_lo:[1,0,0] neg_hi:[1,0,0]
	v_permlane32_swap_b32_e32 v165, v167
	v_pk_fma_f32 v[116:117], v[14:15], v[244:245], v[116:117] op_sel_hi:[1,0,1]
	v_fma_f32 v168, v128, v3, v158
	v_pk_fma_f32 v[102:103], v[16:17], v[244:245], v[102:103] op_sel:[0,1,0] neg_lo:[1,0,0] neg_hi:[1,0,0]
	v_fma_f32 v170, v130, v11, v164
	v_pk_fma_f32 v[118:119], v[16:17], v[244:245], v[118:119] op_sel_hi:[1,0,1]
	v_fma_f32 v169, v128, v7, v159
	v_fma_f32 v171, v130, v17, v165
	v_fma_f32 v132, -v129, v7, v168
	v_fma_f32 v134, -v131, v17, v170
	v_fma_f32 v133, v129, v3, v169
	v_fma_f32 v135, v131, v11, v171
	v_cndmask_b32_e64 v136, v128, v132, s[8:9]
	v_cndmask_b32_e64 v137, v129, v133, s[8:9]
	v_cndmask_b32_e64 v156, v130, v134, s[8:9]
	v_cndmask_b32_e64 v157, v131, v135, s[8:9]
	v_fma_f32 v168, v132, v3, v160
	v_fma_f32 v170, v134, v11, v166
	v_fma_f32 v169, v132, v7, v161
	v_fma_f32 v171, v134, v17, v167
	v_fma_f32 v128, -v133, v7, v168
	v_fma_f32 v130, -v135, v17, v170
	v_fma_f32 v129, v133, v3, v169
	v_fma_f32 v131, v135, v11, v171
	v_pk_fma_f32 v[72:73], v[0:1], v[136:137], v[72:73] op_sel_hi:[1,0,1]
	v_mov_b32_e32 v158, v79
	v_pk_fma_f32 v[88:89], v[0:1], v[136:137], v[88:89] op_sel:[0,1,0]
	v_mov_b32_e32 v160, v79
	v_pk_fma_f32 v[74:75], v[2:3], v[136:137], v[74:75] op_sel_hi:[1,0,1]
	v_mov_b32_e32 v159, v95
	v_pk_fma_f32 v[90:91], v[2:3], v[136:137], v[90:91] op_sel:[0,1,0]
	v_mov_b32_e32 v161, v95
	v_pk_fma_f32 v[104:105], v[8:9], v[156:157], v[104:105] op_sel_hi:[1,0,1]
	v_mov_b32_e32 v164, v111
	v_pk_fma_f32 v[120:121], v[8:9], v[156:157], v[120:121] op_sel:[0,1,0]
	v_mov_b32_e32 v166, v111
	v_pk_fma_f32 v[106:107], v[10:11], v[156:157], v[106:107] op_sel_hi:[1,0,1]
	v_mov_b32_e32 v165, v127
	v_pk_fma_f32 v[122:123], v[10:11], v[156:157], v[122:123] op_sel:[0,1,0]
	v_mov_b32_e32 v167, v127
	v_pk_fma_f32 v[72:73], v[4:5], v[136:137], v[72:73] op_sel:[0,1,0] neg_lo:[1,0,0] neg_hi:[1,0,0]
	s_nop 1
	v_pk_fma_f32 v[88:89], v[4:5], v[136:137], v[88:89] op_sel_hi:[1,0,1]
	v_permlane32_swap_b32_e32 v158, v160
	v_pk_fma_f32 v[74:75], v[6:7], v[136:137], v[74:75] op_sel:[0,1,0] neg_lo:[1,0,0] neg_hi:[1,0,0]
	v_permlane32_swap_b32_e32 v159, v161
	v_pk_fma_f32 v[90:91], v[6:7], v[136:137], v[90:91] op_sel_hi:[1,0,1]
	v_permlane32_swap_b32_e32 v164, v166
	v_pk_fma_f32 v[104:105], v[14:15], v[156:157], v[104:105] op_sel:[0,1,0] neg_lo:[1,0,0] neg_hi:[1,0,0]
	v_permlane32_swap_b32_e32 v165, v167
	v_pk_fma_f32 v[120:121], v[14:15], v[156:157], v[120:121] op_sel_hi:[1,0,1]
	v_fma_f32 v168, v128, v3, v158
	v_pk_fma_f32 v[106:107], v[16:17], v[156:157], v[106:107] op_sel:[0,1,0] neg_lo:[1,0,0] neg_hi:[1,0,0]
	v_fma_f32 v170, v130, v11, v164
	v_pk_fma_f32 v[122:123], v[16:17], v[156:157], v[122:123] op_sel_hi:[1,0,1]
	v_fma_f32 v169, v128, v7, v159
	v_fma_f32 v171, v130, v17, v165
	v_fma_f32 v132, -v129, v7, v168
	v_fma_f32 v134, -v131, v17, v170
	v_fma_f32 v133, v129, v3, v169
	v_fma_f32 v135, v131, v11, v171
	v_cndmask_b32_e64 v172, v128, v132, s[8:9]
	v_cndmask_b32_e64 v173, v129, v133, s[8:9]
	v_cndmask_b32_e64 v244, v130, v134, s[8:9]
	v_cndmask_b32_e64 v245, v131, v135, s[8:9]
	v_fma_f32 v168, v132, v3, v160
	v_fma_f32 v170, v134, v11, v166
	v_fma_f32 v169, v132, v7, v161
	v_fma_f32 v171, v134, v17, v167
	v_fma_f32 v128, -v133, v7, v168
	v_fma_f32 v130, -v135, v17, v170
	v_fma_f32 v129, v133, v3, v169
	v_fma_f32 v131, v135, v11, v171
	v_pk_fma_f32 v[76:77], v[0:1], v[172:173], v[76:77] op_sel_hi:[1,0,1]
	v_pk_fma_f32 v[92:93], v[0:1], v[172:173], v[92:93] op_sel:[0,1,0]
	v_pk_fma_f32 v[78:79], v[2:3], v[172:173], v[78:79] op_sel_hi:[1,0,1]
	v_pk_fma_f32 v[94:95], v[2:3], v[172:173], v[94:95] op_sel:[0,1,0]
	v_pk_fma_f32 v[108:109], v[8:9], v[244:245], v[108:109] op_sel_hi:[1,0,1]
	v_pk_fma_f32 v[124:125], v[8:9], v[244:245], v[124:125] op_sel:[0,1,0]
	v_pk_fma_f32 v[110:111], v[10:11], v[244:245], v[110:111] op_sel_hi:[1,0,1]
	v_pk_fma_f32 v[126:127], v[10:11], v[244:245], v[126:127] op_sel:[0,1,0]
	v_pk_fma_f32 v[76:77], v[4:5], v[172:173], v[76:77] op_sel:[0,1,0] neg_lo:[1,0,0] neg_hi:[1,0,0]
	v_pk_fma_f32 v[92:93], v[4:5], v[172:173], v[92:93] op_sel_hi:[1,0,1]
	v_pk_fma_f32 v[78:79], v[6:7], v[172:173], v[78:79] op_sel:[0,1,0] neg_lo:[1,0,0] neg_hi:[1,0,0]
	v_pk_fma_f32 v[94:95], v[6:7], v[172:173], v[94:95] op_sel_hi:[1,0,1]
	v_pk_fma_f32 v[108:109], v[14:15], v[244:245], v[108:109] op_sel:[0,1,0] neg_lo:[1,0,0] neg_hi:[1,0,0]
	v_pk_fma_f32 v[124:125], v[14:15], v[244:245], v[124:125] op_sel_hi:[1,0,1]
	v_pk_fma_f32 v[110:111], v[16:17], v[244:245], v[110:111] op_sel:[0,1,0] neg_lo:[1,0,0] neg_hi:[1,0,0]
	v_pk_fma_f32 v[126:127], v[16:17], v[244:245], v[126:127] op_sel_hi:[1,0,1]
	v_cvt_pk_bf16_f32 v56, v64, v80
	ds_write_b32 v229, v56 offset:0
	v_cvt_pk_bf16_f32 v57, v96, v112
	ds_write_b32 v229, v57 offset:128
	v_cvt_pk_bf16_f32 v58, v65, v81
	ds_write_b32 v229, v58 offset:272
	v_cvt_pk_bf16_f32 v59, v97, v113
	ds_write_b32 v229, v59 offset:400
	v_cvt_pk_bf16_f32 v56, v66, v82
	ds_write_b32 v229, v56 offset:544
	v_cvt_pk_bf16_f32 v57, v98, v114
	ds_write_b32 v229, v57 offset:672
	v_cvt_pk_bf16_f32 v58, v67, v83
	ds_write_b32 v229, v58 offset:816
	v_cvt_pk_bf16_f32 v59, v99, v115
	ds_write_b32 v229, v59 offset:944
	v_cvt_pk_bf16_f32 v56, v68, v84
	ds_write_b32 v229, v56 offset:2176
	v_cvt_pk_bf16_f32 v57, v100, v116
	ds_write_b32 v229, v57 offset:2304
	v_cvt_pk_bf16_f32 v58, v69, v85
	ds_write_b32 v229, v58 offset:2448
	v_cvt_pk_bf16_f32 v59, v101, v117
	ds_write_b32 v229, v59 offset:2576
	v_cvt_pk_bf16_f32 v56, v70, v86
	ds_write_b32 v229, v56 offset:2720
	v_cvt_pk_bf16_f32 v57, v102, v118
	ds_write_b32 v229, v57 offset:2848
	v_cvt_pk_bf16_f32 v58, v71, v87
	ds_write_b32 v229, v58 offset:2992
	v_cvt_pk_bf16_f32 v59, v103, v119
	ds_write_b32 v229, v59 offset:3120
	v_cvt_pk_bf16_f32 v56, v72, v88
	ds_write_b32 v229, v56 offset:4352
	v_cvt_pk_bf16_f32 v57, v104, v120
	ds_write_b32 v229, v57 offset:4480
	v_cvt_pk_bf16_f32 v58, v73, v89
	ds_write_b32 v229, v58 offset:4624
	v_cvt_pk_bf16_f32 v59, v105, v121
	ds_write_b32 v229, v59 offset:4752
	v_cvt_pk_bf16_f32 v56, v74, v90
	ds_write_b32 v229, v56 offset:4896
	v_cvt_pk_bf16_f32 v57, v106, v122
	ds_write_b32 v229, v57 offset:5024
	v_cvt_pk_bf16_f32 v58, v75, v91
	ds_write_b32 v229, v58 offset:5168
	v_cvt_pk_bf16_f32 v59, v107, v123
	ds_write_b32 v229, v59 offset:5296
	v_cvt_pk_bf16_f32 v56, v76, v92
	ds_write_b32 v229, v56 offset:6528
	v_cvt_pk_bf16_f32 v57, v108, v124
	ds_write_b32 v229, v57 offset:6656
	v_cvt_pk_bf16_f32 v58, v77, v93
	ds_write_b32 v229, v58 offset:6800
	v_cvt_pk_bf16_f32 v59, v109, v125
	ds_write_b32 v229, v59 offset:6928
	v_cvt_pk_bf16_f32 v56, v78, v94
	ds_write_b32 v229, v56 offset:7072
	v_cvt_pk_bf16_f32 v57, v110, v126
	ds_write_b32 v229, v57 offset:7200
	v_cvt_pk_bf16_f32 v58, v79, v95
	ds_write_b32 v229, v58 offset:7344
	v_cvt_pk_bf16_f32 v59, v111, v127
	ds_write_b32 v229, v59 offset:7472
	ds_read_b128 v[164:167], v230 offset:0
	ds_read_b128 v[168:171], v230 offset:64
	ds_read_b128 v[156:159], v230 offset:128
	ds_read_b128 v[132:135], v230 offset:192
	ds_read_b32 v56, v232 offset:0
	ds_read_b32 v57, v232 offset:64
	ds_read_b32 v58, v232 offset:128
	ds_read_b32 v59, v232 offset:192
	s_waitcnt lgkmcnt(7)
	v_mfma_f32_16x16x32_bf16 v[250:253], v[164:167], v[208:211], 0
	s_waitcnt lgkmcnt(6)
	v_mfma_f32_16x16x32_bf16 v[250:253], v[168:171], v[212:215], v[250:253]
	s_waitcnt lgkmcnt(5)
	v_mfma_f32_16x16x32_bf16 v[250:253], v[156:159], v[216:219], v[250:253]
	s_waitcnt lgkmcnt(4)
	v_mfma_f32_16x16x32_bf16 v[250:253], v[132:135], v[220:223], v[250:253]
	s_waitcnt lgkmcnt(0)
	s_nop 7
	s_nop 1
	v_fma_f32 v250, v224, v56, v250
	v_fma_f32 v251, v224, v57, v251
	v_fma_f32 v252, v224, v58, v252
	v_fma_f32 v253, v224, v59, v253
	v_mul_f32_e32 v60, 0x3d372713, v250
	v_mul_f32_e32 v172, 0x3d372713, v251
	v_mul_f32_e32 v173, 0x3d372713, v252
	v_mul_f32_e32 v245, 0x3d372713, v253
	v_mul_f32_e32 v60, v250, v60
	v_mul_f32_e32 v172, v251, v172
	v_mul_f32_e32 v173, v252, v173
	v_mul_f32_e32 v245, v253, v245
	v_fma_f32 v60, v250, v60, v250
	v_fma_f32 v172, v251, v172, v251
	v_fma_f32 v173, v252, v173, v252
	v_fma_f32 v245, v253, v245, v253
	v_mul_f32_e32 v60, 0x40135761, v60
	v_mul_f32_e32 v172, 0x40135761, v172
	v_mul_f32_e32 v173, 0x40135761, v173
	v_mul_f32_e32 v245, 0x40135761, v245
	v_exp_f32_e32 v60, v60
	v_exp_f32_e32 v172, v172
	v_exp_f32_e32 v173, v173
	v_exp_f32_e32 v245, v245
	s_nop 0
	v_add_f32_e32 v60, 1.0, v60
	v_add_f32_e32 v172, 1.0, v172
	v_add_f32_e32 v173, 1.0, v173
	v_add_f32_e32 v245, 1.0, v245
	v_rcp_f32_e32 v60, v60
	v_rcp_f32_e32 v172, v172
	v_rcp_f32_e32 v173, v173
	v_rcp_f32_e32 v245, v245
	s_nop 0
	v_fma_f32 v250, -v60, v250, v250
	v_fma_f32 v251, -v172, v251, v251
	v_fma_f32 v252, -v173, v252, v252
	v_fma_f32 v253, -v245, v253, v253
	v_cvt_pk_bf16_f32 v250, v250, 0
	v_cvt_pk_bf16_f32 v251, v251, 0
	v_cvt_pk_bf16_f32 v252, v252, 0
	v_cvt_pk_bf16_f32 v253, v253, 0
	s_cmp_lg_u32 s35, 0
	s_cselect_b32 s4, 0, -1
	s_mov_b32 exec_hi, s4
	global_store_short v233, v250, s[86:87]
	global_store_short v241, v251, s[86:87]
	global_store_short v242, v252, s[86:87]
	global_store_short v243, v253, s[86:87]
	s_mov_b32 exec_hi, -1
	s_cmp_lg_u32 s35, 0
	s_cbranch_scc1 .Ls5b_ep_skip0
	ds_read_b128 v[164:167], v230 offset:4352
	ds_read_b128 v[168:171], v230 offset:4416
	ds_read_b128 v[156:159], v230 offset:4480
	ds_read_b128 v[132:135], v230 offset:4544
	ds_read_b32 v56, v232 offset:1024
	ds_read_b32 v57, v232 offset:1088
	ds_read_b32 v58, v232 offset:1152
	ds_read_b32 v59, v232 offset:1216
	s_waitcnt lgkmcnt(7)
	v_mfma_f32_16x16x32_bf16 v[250:253], v[164:167], v[208:211], 0
	s_waitcnt lgkmcnt(6)
	v_mfma_f32_16x16x32_bf16 v[250:253], v[168:171], v[212:215], v[250:253]
	s_waitcnt lgkmcnt(5)
	v_mfma_f32_16x16x32_bf16 v[250:253], v[156:159], v[216:219], v[250:253]
	s_waitcnt lgkmcnt(4)
	v_mfma_f32_16x16x32_bf16 v[250:253], v[132:135], v[220:223], v[250:253]
	s_waitcnt lgkmcnt(0)
	s_nop 7
	s_nop 1
	v_fma_f32 v250, v224, v56, v250
	v_fma_f32 v251, v224, v57, v251
	v_fma_f32 v252, v224, v58, v252
	v_fma_f32 v253, v224, v59, v253
	v_mul_f32_e32 v60, 0x3d372713, v250
	v_mul_f32_e32 v172, 0x3d372713, v251
	v_mul_f32_e32 v173, 0x3d372713, v252
	v_mul_f32_e32 v245, 0x3d372713, v253
	v_mul_f32_e32 v60, v250, v60
	v_mul_f32_e32 v172, v251, v172
	v_mul_f32_e32 v173, v252, v173
	v_mul_f32_e32 v245, v253, v245
	v_fma_f32 v60, v250, v60, v250
	v_fma_f32 v172, v251, v172, v251
	v_fma_f32 v173, v252, v173, v252
	v_fma_f32 v245, v253, v245, v253
	v_mul_f32_e32 v60, 0x40135761, v60
	v_mul_f32_e32 v172, 0x40135761, v172
	v_mul_f32_e32 v173, 0x40135761, v173
	v_mul_f32_e32 v245, 0x40135761, v245
	v_exp_f32_e32 v60, v60
	v_exp_f32_e32 v172, v172
	v_exp_f32_e32 v173, v173
	v_exp_f32_e32 v245, v245
	s_nop 0
	v_add_f32_e32 v60, 1.0, v60
	v_add_f32_e32 v172, 1.0, v172
	v_add_f32_e32 v173, 1.0, v173
	v_add_f32_e32 v245, 1.0, v245
	v_rcp_f32_e32 v60, v60
	v_rcp_f32_e32 v172, v172
	v_rcp_f32_e32 v173, v173
	v_rcp_f32_e32 v245, v245
	s_nop 0
	v_fma_f32 v250, -v60, v250, v250
	v_fma_f32 v251, -v172, v251, v251
	v_fma_f32 v252, -v173, v252, v252
	v_fma_f32 v253, -v245, v253, v253
	v_cvt_pk_bf16_f32 v250, v250, 0
	v_cvt_pk_bf16_f32 v251, v251, 0
	v_cvt_pk_bf16_f32 v252, v252, 0
	v_cvt_pk_bf16_f32 v253, v253, 0
	global_store_short v233, v250, s[88:89]
	global_store_short v241, v251, s[88:89]
	global_store_short v242, v252, s[88:89]
	global_store_short v243, v253, s[88:89]
.Ls5b_ep_skip0:
	s_cmp_lg_u32 s35, 0
	s_cbranch_scc1 .Ls5b_item_end
	s_add_i32 s4, s31, 32
	s_lshl_b32 s4, s4, 11
	s_add_u32 s86, s12, s4
	s_addc_u32 s87, s13, 0
	s_add_u32 s88, s86, 0x8000
	s_addc_u32 s89, s87, 0
	v_fmamk_f32 v56, v195, 0x3a800000, v254
	v_rsq_f32_e32 v56, v56
	s_nop 0
	v_pk_mul_f32 v[148:149], v[186:187], v[56:57] op_sel_hi:[1,0]
	v_pk_mul_f32 v[150:151], v[188:189], v[56:57] op_sel_hi:[1,0]
	v_pk_mul_f32 v[152:153], v[190:191], v[56:57] op_sel_hi:[1,0]
	v_pk_mul_f32 v[154:155], v[192:193], v[56:57] op_sel_hi:[1,0]
	v_pk_mul_f32 v[148:149], v[140:141], v[148:149]
	v_pk_mul_f32 v[150:151], v[142:143], v[150:151]
	v_pk_mul_f32 v[152:153], v[144:145], v[152:153]
	v_pk_mul_f32 v[154:155], v[146:147], v[154:155]
	global_load_dwordx4 v[186:189], v227, s[94:95]
	global_load_dwordx4 v[190:193], v227, s[94:95] offset:16
	global_load_dword v195, v228, s[92:93] offset:128
	ds_write_b128 v231, v[148:151] offset:0
	ds_write_b128 v231, v[152:155] offset:16
	s_nop 1
	v_mfma_f32_32x32x2_f32 v[64:79], v148, v24, 0
	v_mfma_f32_32x32x2_f32 v[80:95], v148, v32, 0
	v_mfma_f32_32x32x2_f32 v[96:111], v148, v40, 0
	v_mfma_f32_32x32x2_f32 v[112:127], v148, v48, 0
	v_mfma_f32_32x32x2_f32 v[64:79], v149, v25, v[64:79]
	v_mfma_f32_32x32x2_f32 v[80:95], v149, v33, v[80:95]
	v_mfma_f32_32x32x2_f32 v[96:111], v149, v41, v[96:111]
	v_mfma_f32_32x32x2_f32 v[112:127], v149, v49, v[112:127]
	v_mfma_f32_32x32x2_f32 v[64:79], v150, v26, v[64:79]
	v_mfma_f32_32x32x2_f32 v[80:95], v150, v34, v[80:95]
	v_mfma_f32_32x32x2_f32 v[96:111], v150, v42, v[96:111]
	v_mfma_f32_32x32x2_f32 v[112:127], v150, v50, v[112:127]
	v_mfma_f32_32x32x2_f32 v[64:79], v151, v27, v[64:79]
	v_mfma_f32_32x32x2_f32 v[80:95], v151, v35, v[80:95]
	v_mfma_f32_32x32x2_f32 v[96:111], v151, v43, v[96:111]
	v_mfma_f32_32x32x2_f32 v[112:127], v151, v51, v[112:127]
	v_mfma_f32_32x32x2_f32 v[64:79], v152, v28, v[64:79]
	v_mfma_f32_32x32x2_f32 v[80:95], v152, v36, v[80:95]
	v_mfma_f32_32x32x2_f32 v[96:111], v152, v44, v[96:111]
	v_mfma_f32_32x32x2_f32 v[112:127], v152, v52, v[112:127]
	v_mfma_f32_32x32x2_f32 v[64:79], v153, v29, v[64:79]
	v_mfma_f32_32x32x2_f32 v[80:95], v153, v37, v[80:95]
	v_mfma_f32_32x32x2_f32 v[96:111], v153, v45, v[96:111]
	v_mfma_f32_32x32x2_f32 v[112:127], v153, v53, v[112:127]
	v_mfma_f32_32x32x2_f32 v[64:79], v154, v30, v[64:79]
	v_mfma_f32_32x32x2_f32 v[80:95], v154, v38, v[80:95]
	v_mfma_f32_32x32x2_f32 v[96:111], v154, v46, v[96:111]
	v_mfma_f32_32x32x2_f32 v[112:127], v154, v54, v[112:127]
	v_mfma_f32_32x32x2_f32 v[64:79], v155, v31, v[64:79]
	v_mfma_f32_32x32x2_f32 v[80:95], v155, v39, v[80:95]
	v_mfma_f32_32x32x2_f32 v[96:111], v155, v47, v[96:111]
	v_mfma_f32_32x32x2_f32 v[112:127], v155, v55, v[112:127]
	s_nop 7
	s_nop 7
	s_nop 1
	v_fmac_f32_e32 v65, v64, v0
	v_fmac_f32_e32 v97, v96, v8
	v_fmac_f32_e32 v69, v68, v0
	v_fmac_f32_e32 v101, v100, v8
	v_fmac_f32_e32 v73, v72, v0
	v_fmac_f32_e32 v105, v104, v8
	v_fmac_f32_e32 v77, v76, v0
	v_fmac_f32_e32 v109, v108, v8
	v_fmac_f32_e32 v81, v64, v4
	v_fmac_f32_e32 v113, v96, v14
	v_fmac_f32_e32 v85, v68, v4
	v_fmac_f32_e32 v117, v100, v14
	v_fmac_f32_e32 v89, v72, v4
	v_fmac_f32_e32 v121, v104, v14
	v_fmac_f32_e32 v93, v76, v4
	v_fmac_f32_e32 v125, v108, v14
	v_fma_f32 v65, -v80, v4, v65
	v_fma_f32 v97, -v112, v14, v97
	v_fma_f32 v69, -v84, v4, v69
	v_fma_f32 v101, -v116, v14, v101
	v_fma_f32 v73, -v88, v4, v73
	v_fma_f32 v105, -v120, v14, v105
	v_fma_f32 v77, -v92, v4, v77
	v_fma_f32 v109, -v124, v14, v109
	v_fmac_f32_e32 v81, v80, v0
	v_fmac_f32_e32 v113, v112, v8
	v_fmac_f32_e32 v85, v84, v0
	v_fmac_f32_e32 v117, v116, v8
	v_fmac_f32_e32 v89, v88, v0
	v_fmac_f32_e32 v121, v120, v8
	v_fmac_f32_e32 v93, v92, v0
	v_fmac_f32_e32 v125, v124, v8
	v_fmac_f32_e32 v66, v65, v0
	v_fmac_f32_e32 v98, v97, v8
	v_fmac_f32_e32 v70, v69, v0
	v_fmac_f32_e32 v102, v101, v8
	v_fmac_f32_e32 v74, v73, v0
	v_fmac_f32_e32 v106, v105, v8
	v_fmac_f32_e32 v78, v77, v0
	v_fmac_f32_e32 v110, v109, v8
	v_fmac_f32_e32 v82, v65, v4
	v_fmac_f32_e32 v114, v97, v14
	v_fmac_f32_e32 v86, v69, v4
	v_fmac_f32_e32 v118, v101, v14
	v_fmac_f32_e32 v90, v73, v4
	v_fmac_f32_e32 v122, v105, v14
	v_fmac_f32_e32 v94, v77, v4
	v_fmac_f32_e32 v126, v109, v14
	v_fma_f32 v66, -v81, v4, v66
	v_fma_f32 v98, -v113, v14, v98
	v_fma_f32 v70, -v85, v4, v70
	v_fma_f32 v102, -v117, v14, v102
	v_fma_f32 v74, -v89, v4, v74
	v_fma_f32 v106, -v121, v14, v106
	v_fma_f32 v78, -v93, v4, v78
	v_fma_f32 v110, -v125, v14, v110
	v_fmac_f32_e32 v82, v81, v0
	v_fmac_f32_e32 v114, v113, v8
	v_fmac_f32_e32 v86, v85, v0
	v_fmac_f32_e32 v118, v117, v8
	v_fmac_f32_e32 v90, v89, v0
	v_fmac_f32_e32 v122, v121, v8
	v_fmac_f32_e32 v94, v93, v0
	v_fmac_f32_e32 v126, v125, v8
	v_fmac_f32_e32 v67, v66, v0
	v_fmac_f32_e32 v99, v98, v8
	v_fmac_f32_e32 v71, v70, v0
	v_fmac_f32_e32 v103, v102, v8
	v_fmac_f32_e32 v75, v74, v0
	v_fmac_f32_e32 v107, v106, v8
	v_fmac_f32_e32 v79, v78, v0
	v_fmac_f32_e32 v111, v110, v8
	v_fmac_f32_e32 v83, v66, v4
	v_fmac_f32_e32 v115, v98, v14
	v_fmac_f32_e32 v87, v70, v4
	v_fmac_f32_e32 v119, v102, v14
	v_fmac_f32_e32 v91, v74, v4
	v_fmac_f32_e32 v123, v106, v14
	v_fmac_f32_e32 v95, v78, v4
	v_fmac_f32_e32 v127, v110, v14
	v_fma_f32 v67, -v82, v4, v67
	v_fma_f32 v99, -v114, v14, v99
	v_fma_f32 v71, -v86, v4, v71
	v_fma_f32 v103, -v118, v14, v103
	v_fma_f32 v75, -v90, v4, v75
	v_fma_f32 v107, -v122, v14, v107
	v_fma_f32 v79, -v94, v4, v79
	v_fma_f32 v111, -v126, v14, v111
	v_fmac_f32_e32 v83, v82, v0
	v_fmac_f32_e32 v115, v114, v8
	v_fmac_f32_e32 v87, v86, v0
	v_fmac_f32_e32 v119, v118, v8
	v_fmac_f32_e32 v91, v90, v0
	v_fmac_f32_e32 v123, v122, v8
	v_fmac_f32_e32 v95, v94, v0
	v_fmac_f32_e32 v127, v126, v8
	v_mov_b32_e32 v158, v67
	v_mov_b32_e32 v160, v67
	v_mov_b32_e32 v159, v83
	v_mov_b32_e32 v161, v83
	v_mov_b32_e32 v164, v99
	v_mov_b32_e32 v166, v99
	v_mov_b32_e32 v165, v115
	v_mov_b32_e32 v167, v115
	s_nop 1
	v_permlane32_swap_b32_e32 v158, v160
	v_permlane32_swap_b32_e32 v159, v161
	v_permlane32_swap_b32_e32 v164, v166
	v_permlane32_swap_b32_e32 v165, v167
	v_fma_f32 v168, v128, v3, v158
	v_fma_f32 v170, v130, v11, v164
	v_fma_f32 v169, v128, v7, v159
	v_fma_f32 v171, v130, v17, v165
	v_fma_f32 v132, -v129, v7, v168
	v_fma_f32 v134, -v131, v17, v170
	v_fma_f32 v133, v129, v3, v169
	v_fma_f32 v135, v131, v11, v171
	v_cndmask_b32_e64 v136, v128, v132, s[8:9]
	v_cndmask_b32_e64 v137, v129, v133, s[8:9]
	v_cndmask_b32_e64 v156, v130, v134, s[8:9]
	v_cndmask_b32_e64 v157, v131, v135, s[8:9]
	v_fma_f32 v168, v132, v3, v160
	v_fma_f32 v170, v134, v11, v166
	v_fma_f32 v169, v132, v7, v161
	v_fma_f32 v171, v134, v17, v167
	v_fma_f32 v128, -v133, v7, v168
	v_fma_f32 v130, -v135, v17, v170
	v_fma_f32 v129, v133, v3, v169
	v_fma_f32 v131, v135, v11, v171
	v_mov_b32_e32 v246, v128
	v_mov_b32_e32 v247, v129
	v_mov_b32_e32 v248, v130
	v_mov_b32_e32 v249, v131
	v_pk_fma_f32 v[64:65], v[0:1], v[136:137], v[64:65] op_sel_hi:[1,0,1]
	v_mov_b32_e32 v158, v71
	v_pk_fma_f32 v[80:81], v[0:1], v[136:137], v[80:81] op_sel:[0,1,0]
	v_mov_b32_e32 v160, v71
	v_pk_fma_f32 v[66:67], v[2:3], v[136:137], v[66:67] op_sel_hi:[1,0,1]
	v_mov_b32_e32 v159, v87
	v_pk_fma_f32 v[82:83], v[2:3], v[136:137], v[82:83] op_sel:[0,1,0]
	v_mov_b32_e32 v161, v87
	v_pk_fma_f32 v[96:97], v[8:9], v[156:157], v[96:97] op_sel_hi:[1,0,1]
	v_mov_b32_e32 v164, v103
	v_pk_fma_f32 v[112:113], v[8:9], v[156:157], v[112:113] op_sel:[0,1,0]
	v_mov_b32_e32 v166, v103
	v_pk_fma_f32 v[98:99], v[10:11], v[156:157], v[98:99] op_sel_hi:[1,0,1]
	v_mov_b32_e32 v165, v119
	v_pk_fma_f32 v[114:115], v[10:11], v[156:157], v[114:115] op_sel:[0,1,0]
	v_mov_b32_e32 v167, v119
	v_pk_fma_f32 v[64:65], v[4:5], v[136:137], v[64:65] op_sel:[0,1,0] neg_lo:[1,0,0] neg_hi:[1,0,0]
	s_nop 1
	v_pk_fma_f32 v[80:81], v[4:5], v[136:137], v[80:81] op_sel_hi:[1,0,1]
	v_permlane32_swap_b32_e32 v158, v160
	v_pk_fma_f32 v[66:67], v[6:7], v[136:137], v[66:67] op_sel:[0,1,0] neg_lo:[1,0,0] neg_hi:[1,0,0]
	v_permlane32_swap_b32_e32 v159, v161
	v_pk_fma_f32 v[82:83], v[6:7], v[136:137], v[82:83] op_sel_hi:[1,0,1]
	v_permlane32_swap_b32_e32 v164, v166
	v_pk_fma_f32 v[96:97], v[14:15], v[156:157], v[96:97] op_sel:[0,1,0] neg_lo:[1,0,0] neg_hi:[1,0,0]
	v_permlane32_swap_b32_e32 v165, v167
	v_pk_fma_f32 v[112:113], v[14:15], v[156:157], v[112:113] op_sel_hi:[1,0,1]
	v_fma_f32 v168, v128, v3, v158
	v_pk_fma_f32 v[98:99], v[16:17], v[156:157], v[98:99] op_sel:[0,1,0] neg_lo:[1,0,0] neg_hi:[1,0,0]
	v_fma_f32 v170, v130, v11, v164
	v_pk_fma_f32 v[114:115], v[16:17], v[156:157], v[114:115] op_sel_hi:[1,0,1]
	v_fma_f32 v169, v128, v7, v159
	v_fma_f32 v171, v130, v17, v165
	v_fma_f32 v132, -v129, v7, v168
	v_fma_f32 v134, -v131, v17, v170
	v_fma_f32 v133, v129, v3, v169
	v_fma_f32 v135, v131, v11, v171
	v_cndmask_b32_e64 v172, v128, v132, s[8:9]
	v_cndmask_b32_e64 v173, v129, v133, s[8:9]
	v_cndmask_b32_e64 v244, v130, v134, s[8:9]
	v_cndmask_b32_e64 v245, v131, v135, s[8:9]
	v_fma_f32 v168, v132, v3, v160
	v_fma_f32 v170, v134, v11, v166
	v_fma_f32 v169, v132, v7, v161
	v_fma_f32 v171, v134, v17, v167
	v_fma_f32 v128, -v133, v7, v168
	v_fma_f32 v130, -v135, v17, v170
	v_fma_f32 v129, v133, v3, v169
	v_fma_f32 v131, v135, v11, v171
	v_pk_fma_f32 v[68:69], v[0:1], v[172:173], v[68:69] op_sel_hi:[1,0,1]
	v_mov_b32_e32 v158, v75
	v_pk_fma_f32 v[84:85], v[0:1], v[172:173], v[84:85] op_sel:[0,1,0]
	v_mov_b32_e32 v160, v75
	v_pk_fma_f32 v[70:71], v[2:3], v[172:173], v[70:71] op_sel_hi:[1,0,1]
	v_mov_b32_e32 v159, v91
	v_pk_fma_f32 v[86:87], v[2:3], v[172:173], v[86:87] op_sel:[0,1,0]
	v_mov_b32_e32 v161, v91
	v_pk_fma_f32 v[100:101], v[8:9], v[244:245], v[100:101] op_sel_hi:[1,0,1]
	v_mov_b32_e32 v164, v107
	v_pk_fma_f32 v[116:117], v[8:9], v[244:245], v[116:117] op_sel:[0,1,0]
	v_mov_b32_e32 v166, v107
	v_pk_fma_f32 v[102:103], v[10:11], v[244:245], v[102:103] op_sel_hi:[1,0,1]
	v_mov_b32_e32 v165, v123
	v_pk_fma_f32 v[118:119], v[10:11], v[244:245], v[118:119] op_sel:[0,1,0]
	v_mov_b32_e32 v167, v123
	v_pk_fma_f32 v[68:69], v[4:5], v[172:173], v[68:69] op_sel:[0,1,0] neg_lo:[1,0,0] neg_hi:[1,0,0]
	s_nop 1
	v_pk_fma_f32 v[84:85], v[4:5], v[172:173], v[84:85] op_sel_hi:[1,0,1]
	v_permlane32_swap_b32_e32 v158, v160
	v_pk_fma_f32 v[70:71], v[6:7], v[172:173], v[70:71] op_sel:[0,1,0] neg_lo:[1,0,0] neg_hi:[1,0,0]
	v_permlane32_swap_b32_e32 v159, v161
	v_pk_fma_f32 v[86:87], v[6:7], v[172:173], v[86:87] op_sel_hi:[1,0,1]
	v_permlane32_swap_b32_e32 v164, v166
	v_pk_fma_f32 v[100:101], v[14:15], v[244:245], v[100:101] op_sel:[0,1,0] neg_lo:[1,0,0] neg_hi:[1,0,0]
	v_permlane32_swap_b32_e32 v165, v167
	v_pk_fma_f32 v[116:117], v[14:15], v[244:245], v[116:117] op_sel_hi:[1,0,1]
	v_fma_f32 v168, v128, v3, v158
	v_pk_fma_f32 v[102:103], v[16:17], v[244:245], v[102:103] op_sel:[0,1,0] neg_lo:[1,0,0] neg_hi:[1,0,0]
	v_fma_f32 v170, v130, v11, v164
	v_pk_fma_f32 v[118:119], v[16:17], v[244:245], v[118:119] op_sel_hi:[1,0,1]
	v_fma_f32 v169, v128, v7, v159
	v_fma_f32 v171, v130, v17, v165
	v_fma_f32 v132, -v129, v7, v168
	v_fma_f32 v134, -v131, v17, v170
	v_fma_f32 v133, v129, v3, v169
	v_fma_f32 v135, v131, v11, v171
	v_cndmask_b32_e64 v136, v128, v132, s[8:9]
	v_cndmask_b32_e64 v137, v129, v133, s[8:9]
	v_cndmask_b32_e64 v156, v130, v134, s[8:9]
	v_cndmask_b32_e64 v157, v131, v135, s[8:9]
	v_fma_f32 v168, v132, v3, v160
	v_fma_f32 v170, v134, v11, v166
	v_fma_f32 v169, v132, v7, v161
	v_fma_f32 v171, v134, v17, v167
	v_fma_f32 v128, -v133, v7, v168
	v_fma_f32 v130, -v135, v17, v170
	v_fma_f32 v129, v133, v3, v169
	v_fma_f32 v131, v135, v11, v171
	v_pk_fma_f32 v[72:73], v[0:1], v[136:137], v[72:73] op_sel_hi:[1,0,1]
	v_mov_b32_e32 v158, v79
	v_pk_fma_f32 v[88:89], v[0:1], v[136:137], v[88:89] op_sel:[0,1,0]
	v_mov_b32_e32 v160, v79
	v_pk_fma_f32 v[74:75], v[2:3], v[136:137], v[74:75] op_sel_hi:[1,0,1]
	v_mov_b32_e32 v159, v95
	v_pk_fma_f32 v[90:91], v[2:3], v[136:137], v[90:91] op_sel:[0,1,0]
	v_mov_b32_e32 v161, v95
	v_pk_fma_f32 v[104:105], v[8:9], v[156:157], v[104:105] op_sel_hi:[1,0,1]
	v_mov_b32_e32 v164, v111
	v_pk_fma_f32 v[120:121], v[8:9], v[156:157], v[120:121] op_sel:[0,1,0]
	v_mov_b32_e32 v166, v111
	v_pk_fma_f32 v[106:107], v[10:11], v[156:157], v[106:107] op_sel_hi:[1,0,1]
	v_mov_b32_e32 v165, v127
	v_pk_fma_f32 v[122:123], v[10:11], v[156:157], v[122:123] op_sel:[0,1,0]
	v_mov_b32_e32 v167, v127
	v_pk_fma_f32 v[72:73], v[4:5], v[136:137], v[72:73] op_sel:[0,1,0] neg_lo:[1,0,0] neg_hi:[1,0,0]
	s_nop 1
	v_pk_fma_f32 v[88:89], v[4:5], v[136:137], v[88:89] op_sel_hi:[1,0,1]
	v_permlane32_swap_b32_e32 v158, v160
	v_pk_fma_f32 v[74:75], v[6:7], v[136:137], v[74:75] op_sel:[0,1,0] neg_lo:[1,0,0] neg_hi:[1,0,0]
	v_permlane32_swap_b32_e32 v159, v161
	v_pk_fma_f32 v[90:91], v[6:7], v[136:137], v[90:91] op_sel_hi:[1,0,1]
	v_permlane32_swap_b32_e32 v164, v166
	v_pk_fma_f32 v[104:105], v[14:15], v[156:157], v[104:105] op_sel:[0,1,0] neg_lo:[1,0,0] neg_hi:[1,0,0]
	v_permlane32_swap_b32_e32 v165, v167
	v_pk_fma_f32 v[120:121], v[14:15], v[156:157], v[120:121] op_sel_hi:[1,0,1]
	v_fma_f32 v168, v128, v3, v158
	v_pk_fma_f32 v[106:107], v[16:17], v[156:157], v[106:107] op_sel:[0,1,0] neg_lo:[1,0,0] neg_hi:[1,0,0]
	v_fma_f32 v170, v130, v11, v164
	v_pk_fma_f32 v[122:123], v[16:17], v[156:157], v[122:123] op_sel_hi:[1,0,1]
	v_fma_f32 v169, v128, v7, v159
	v_fma_f32 v171, v130, v17, v165
	v_fma_f32 v132, -v129, v7, v168
	v_fma_f32 v134, -v131, v17, v170
	v_fma_f32 v133, v129, v3, v169
	v_fma_f32 v135, v131, v11, v171
	v_cndmask_b32_e64 v172, v128, v132, s[8:9]
	v_cndmask_b32_e64 v173, v129, v133, s[8:9]
	v_cndmask_b32_e64 v244, v130, v134, s[8:9]
	v_cndmask_b32_e64 v245, v131, v135, s[8:9]
	v_fma_f32 v168, v132, v3, v160
	v_fma_f32 v170, v134, v11, v166
	v_fma_f32 v169, v132, v7, v161
	v_fma_f32 v171, v134, v17, v167
	v_fma_f32 v128, -v133, v7, v168
	v_fma_f32 v130, -v135, v17, v170
	v_fma_f32 v129, v133, v3, v169
	v_fma_f32 v131, v135, v11, v171
	v_pk_fma_f32 v[76:77], v[0:1], v[172:173], v[76:77] op_sel_hi:[1,0,1]
	v_pk_fma_f32 v[92:93], v[0:1], v[172:173], v[92:93] op_sel:[0,1,0]
	v_pk_fma_f32 v[78:79], v[2:3], v[172:173], v[78:79] op_sel_hi:[1,0,1]
	v_pk_fma_f32 v[94:95], v[2:3], v[172:173], v[94:95] op_sel:[0,1,0]
	v_pk_fma_f32 v[108:109], v[8:9], v[244:245], v[108:109] op_sel_hi:[1,0,1]
	v_pk_fma_f32 v[124:125], v[8:9], v[244:245], v[124:125] op_sel:[0,1,0]
	v_pk_fma_f32 v[110:111], v[10:11], v[244:245], v[110:111] op_sel_hi:[1,0,1]
	v_pk_fma_f32 v[126:127], v[10:11], v[244:245], v[126:127] op_sel:[0,1,0]
	v_pk_fma_f32 v[76:77], v[4:5], v[172:173], v[76:77] op_sel:[0,1,0] neg_lo:[1,0,0] neg_hi:[1,0,0]
	v_pk_fma_f32 v[92:93], v[4:5], v[172:173], v[92:93] op_sel_hi:[1,0,1]
	v_pk_fma_f32 v[78:79], v[6:7], v[172:173], v[78:79] op_sel:[0,1,0] neg_lo:[1,0,0] neg_hi:[1,0,0]
	v_pk_fma_f32 v[94:95], v[6:7], v[172:173], v[94:95] op_sel_hi:[1,0,1]
	v_pk_fma_f32 v[108:109], v[14:15], v[244:245], v[108:109] op_sel:[0,1,0] neg_lo:[1,0,0] neg_hi:[1,0,0]
	v_pk_fma_f32 v[124:125], v[14:15], v[244:245], v[124:125] op_sel_hi:[1,0,1]
	v_pk_fma_f32 v[110:111], v[16:17], v[244:245], v[110:111] op_sel:[0,1,0] neg_lo:[1,0,0] neg_hi:[1,0,0]
	v_pk_fma_f32 v[126:127], v[16:17], v[244:245], v[126:127] op_sel_hi:[1,0,1]
	v_cvt_pk_bf16_f32 v56, v64, v80
	ds_write_b32 v229, v56 offset:0
	v_cvt_pk_bf16_f32 v57, v96, v112
	ds_write_b32 v229, v57 offset:128
	v_cvt_pk_bf16_f32 v58, v65, v81
	ds_write_b32 v229, v58 offset:272
	v_cvt_pk_bf16_f32 v59, v97, v113
	ds_write_b32 v229, v59 offset:400
	v_cvt_pk_bf16_f32 v56, v66, v82
	ds_write_b32 v229, v56 offset:544
	v_cvt_pk_bf16_f32 v57, v98, v114
	ds_write_b32 v229, v57 offset:672
	v_cvt_pk_bf16_f32 v58, v67, v83
	ds_write_b32 v229, v58 offset:816
	v_cvt_pk_bf16_f32 v59, v99, v115
	ds_write_b32 v229, v59 offset:944
	v_cvt_pk_bf16_f32 v56, v68, v84
	ds_write_b32 v229, v56 offset:2176
	v_cvt_pk_bf16_f32 v57, v100, v116
	ds_write_b32 v229, v57 offset:2304
	v_cvt_pk_bf16_f32 v58, v69, v85
	ds_write_b32 v229, v58 offset:2448
	v_cvt_pk_bf16_f32 v59, v101, v117
	ds_write_b32 v229, v59 offset:2576
	v_cvt_pk_bf16_f32 v56, v70, v86
	ds_write_b32 v229, v56 offset:2720
	v_cvt_pk_bf16_f32 v57, v102, v118
	ds_write_b32 v229, v57 offset:2848
	v_cvt_pk_bf16_f32 v58, v71, v87
	ds_write_b32 v229, v58 offset:2992
	v_cvt_pk_bf16_f32 v59, v103, v119
	ds_write_b32 v229, v59 offset:3120
	v_cvt_pk_bf16_f32 v56, v72, v88
	ds_write_b32 v229, v56 offset:4352
	v_cvt_pk_bf16_f32 v57, v104, v120
	ds_write_b32 v229, v57 offset:4480
	v_cvt_pk_bf16_f32 v58, v73, v89
	ds_write_b32 v229, v58 offset:4624
	v_cvt_pk_bf16_f32 v59, v105, v121
	ds_write_b32 v229, v59 offset:4752
	v_cvt_pk_bf16_f32 v56, v74, v90
	ds_write_b32 v229, v56 offset:4896
	v_cvt_pk_bf16_f32 v57, v106, v122
	ds_write_b32 v229, v57 offset:5024
	v_cvt_pk_bf16_f32 v58, v75, v91
	ds_write_b32 v229, v58 offset:5168
	v_cvt_pk_bf16_f32 v59, v107, v123
	ds_write_b32 v229, v59 offset:5296
	v_cvt_pk_bf16_f32 v56, v76, v92
	ds_write_b32 v229, v56 offset:6528
	v_cvt_pk_bf16_f32 v57, v108, v124
	ds_write_b32 v229, v57 offset:6656
	v_cvt_pk_bf16_f32 v58, v77, v93
	ds_write_b32 v229, v58 offset:6800
	v_cvt_pk_bf16_f32 v59, v109, v125
	ds_write_b32 v229, v59 offset:6928
	v_cvt_pk_bf16_f32 v56, v78, v94
	ds_write_b32 v229, v56 offset:7072
	v_cvt_pk_bf16_f32 v57, v110, v126
	ds_write_b32 v229, v57 offset:7200
	v_cvt_pk_bf16_f32 v58, v79, v95
	ds_write_b32 v229, v58 offset:7344
	v_cvt_pk_bf16_f32 v59, v111, v127
	ds_write_b32 v229, v59 offset:7472
	s_cmp_eq_u32 s83, s82
	s_cbranch_scc1 .Ls5b_nopf
	s_cmpk_gt_i32 s83, 0x7ff
	s_cbranch_scc1 .Ls5b_nopf
	s_lshr_b32 s65, s83, 10
	s_bfe_u32 s66, s83, 0x70003
	s_cmp_eq_u32 s65, s46
	s_cselect_b32 s67, s52, 0
	s_lshl_b32 s4, s65, 22
	s_add_u32 s100, s28, s4
	s_addc_u32 s101, s29, 0
	s_add_i32 s57, s66, -1
	s_max_i32 s57, s57, 0
	s_add_i32 s4, s67, 0
	s_min_i32 s4, s4, s57
	s_lshl_b32 s4, s4, 15
	s_add_u32 s6, s100, s4
	s_addc_u32 s7, s101, 0
	global_load_dwordx2 v[64:65], v207, s[6:7]
	s_add_i32 s4, s67, 1
	s_min_i32 s4, s4, s57
	s_lshl_b32 s4, s4, 15
	s_add_u32 s6, s100, s4
	s_addc_u32 s7, s101, 0
	global_load_dwordx2 v[66:67], v207, s[6:7]
	s_add_i32 s4, s67, 2
	s_min_i32 s4, s4, s57
	s_lshl_b32 s4, s4, 15
	s_add_u32 s6, s100, s4
	s_addc_u32 s7, s101, 0
	global_load_dwordx2 v[68:69], v207, s[6:7]
	s_add_i32 s4, s67, 3
	s_min_i32 s4, s4, s57
	s_lshl_b32 s4, s4, 15
	s_add_u32 s6, s100, s4
	s_addc_u32 s7, s101, 0
	global_load_dwordx2 v[70:71], v207, s[6:7]
	s_add_i32 s4, s67, 4
	s_min_i32 s4, s4, s57
	s_lshl_b32 s4, s4, 15
	s_add_u32 s6, s100, s4
	s_addc_u32 s7, s101, 0
	global_load_dwordx2 v[72:73], v207, s[6:7]
	s_add_i32 s4, s67, 5
	s_min_i32 s4, s4, s57
	s_lshl_b32 s4, s4, 15
	s_add_u32 s6, s100, s4
	s_addc_u32 s7, s101, 0
	global_load_dwordx2 v[74:75], v207, s[6:7]
	s_add_i32 s4, s67, 6
	s_min_i32 s4, s4, s57
	s_lshl_b32 s4, s4, 15
	s_add_u32 s6, s100, s4
	s_addc_u32 s7, s101, 0
	global_load_dwordx2 v[76:77], v207, s[6:7]
	s_add_i32 s4, s67, 7
	s_min_i32 s4, s4, s57
	s_lshl_b32 s4, s4, 15
	s_add_u32 s6, s100, s4
	s_addc_u32 s7, s101, 0
	global_load_dwordx2 v[78:79], v207, s[6:7]
	s_add_i32 s4, s67, 8
	s_min_i32 s4, s4, s57
	s_lshl_b32 s4, s4, 15
	s_add_u32 s6, s100, s4
	s_addc_u32 s7, s101, 0
	global_load_dwordx2 v[80:81], v207, s[6:7]
	s_add_i32 s4, s67, 9
	s_min_i32 s4, s4, s57
	s_lshl_b32 s4, s4, 15
	s_add_u32 s6, s100, s4
	s_addc_u32 s7, s101, 0
	global_load_dwordx2 v[82:83], v207, s[6:7]
	s_add_i32 s4, s67, 10
	s_min_i32 s4, s4, s57
	s_lshl_b32 s4, s4, 15
	s_add_u32 s6, s100, s4
	s_addc_u32 s7, s101, 0
	global_load_dwordx2 v[84:85], v207, s[6:7]
	s_add_i32 s4, s67, 11
	s_min_i32 s4, s4, s57
	s_lshl_b32 s4, s4, 15
	s_add_u32 s6, s100, s4
	s_addc_u32 s7, s101, 0
	global_load_dwordx2 v[86:87], v207, s[6:7]
	s_add_i32 s4, s67, 12
	s_min_i32 s4, s4, s57
	s_lshl_b32 s4, s4, 15
	s_add_u32 s6, s100, s4
	s_addc_u32 s7, s101, 0
	global_load_dwordx2 v[88:89], v207, s[6:7]
	s_add_i32 s4, s67, 13
	s_min_i32 s4, s4, s57
	s_lshl_b32 s4, s4, 15
	s_add_u32 s6, s100, s4
	s_addc_u32 s7, s101, 0
	global_load_dwordx2 v[90:91], v207, s[6:7]
	s_add_i32 s4, s67, 14
	s_min_i32 s4, s4, s57
	s_lshl_b32 s4, s4, 15
	s_add_u32 s6, s100, s4
	s_addc_u32 s7, s101, 0
	global_load_dwordx2 v[92:93], v207, s[6:7]
	s_add_i32 s4, s67, 15
	s_min_i32 s4, s4, s57
	s_lshl_b32 s4, s4, 15
	s_add_u32 s6, s100, s4
	s_addc_u32 s7, s101, 0
	global_load_dwordx2 v[94:95], v207, s[6:7]
	s_add_i32 s4, s67, 16
	s_min_i32 s4, s4, s57
	s_lshl_b32 s4, s4, 15
	s_add_u32 s6, s100, s4
	s_addc_u32 s7, s101, 0
	global_load_dwordx2 v[96:97], v207, s[6:7]
	s_add_i32 s4, s67, 17
	s_min_i32 s4, s4, s57
	s_lshl_b32 s4, s4, 15
	s_add_u32 s6, s100, s4
	s_addc_u32 s7, s101, 0
	global_load_dwordx2 v[98:99], v207, s[6:7]
	s_add_i32 s4, s67, 18
	s_min_i32 s4, s4, s57
	s_lshl_b32 s4, s4, 15
	s_add_u32 s6, s100, s4
	s_addc_u32 s7, s101, 0
	global_load_dwordx2 v[100:101], v207, s[6:7]
	s_add_i32 s4, s67, 19
	s_min_i32 s4, s4, s57
	s_lshl_b32 s4, s4, 15
	s_add_u32 s6, s100, s4
	s_addc_u32 s7, s101, 0
	global_load_dwordx2 v[102:103], v207, s[6:7]
	s_add_i32 s4, s67, 20
	s_min_i32 s4, s4, s57
	s_lshl_b32 s4, s4, 15
	s_add_u32 s6, s100, s4
	s_addc_u32 s7, s101, 0
	global_load_dwordx2 v[104:105], v207, s[6:7]
	s_add_i32 s4, s67, 21
	s_min_i32 s4, s4, s57
	s_lshl_b32 s4, s4, 15
	s_add_u32 s6, s100, s4
	s_addc_u32 s7, s101, 0
	global_load_dwordx2 v[106:107], v207, s[6:7]
	s_add_i32 s4, s67, 22
	s_min_i32 s4, s4, s57
	s_lshl_b32 s4, s4, 15
	s_add_u32 s6, s100, s4
	s_addc_u32 s7, s101, 0
	global_load_dwordx2 v[108:109], v207, s[6:7]
	s_add_i32 s4, s67, 23
	s_min_i32 s4, s4, s57
	s_lshl_b32 s4, s4, 15
	s_add_u32 s6, s100, s4
	s_addc_u32 s7, s101, 0
	global_load_dwordx2 v[110:111], v207, s[6:7]
	s_add_i32 s4, s67, 24
	s_min_i32 s4, s4, s57
	s_lshl_b32 s4, s4, 15
	s_add_u32 s6, s100, s4
	s_addc_u32 s7, s101, 0
	global_load_dwordx2 v[112:113], v207, s[6:7]
	s_add_i32 s4, s67, 25
	s_min_i32 s4, s4, s57
	s_lshl_b32 s4, s4, 15
	s_add_u32 s6, s100, s4
	s_addc_u32 s7, s101, 0
	global_load_dwordx2 v[114:115], v207, s[6:7]
	s_add_i32 s4, s67, 26
	s_min_i32 s4, s4, s57
	s_lshl_b32 s4, s4, 15
	s_add_u32 s6, s100, s4
	s_addc_u32 s7, s101, 0
	global_load_dwordx2 v[116:117], v207, s[6:7]
	s_add_i32 s4, s67, 27
	s_min_i32 s4, s4, s57
	s_lshl_b32 s4, s4, 15
	s_add_u32 s6, s100, s4
	s_addc_u32 s7, s101, 0
	global_load_dwordx2 v[118:119], v207, s[6:7]
	s_add_i32 s4, s67, 28
	s_min_i32 s4, s4, s57
	s_lshl_b32 s4, s4, 15
	s_add_u32 s6, s100, s4
	s_addc_u32 s7, s101, 0
	global_load_dwordx2 v[120:121], v207, s[6:7]
	s_add_i32 s4, s67, 29
	s_min_i32 s4, s4, s57
	s_lshl_b32 s4, s4, 15
	s_add_u32 s6, s100, s4
	s_addc_u32 s7, s101, 0
	global_load_dwordx2 v[122:123], v207, s[6:7]
	s_add_i32 s4, s67, 30
	s_min_i32 s4, s4, s57
	s_lshl_b32 s4, s4, 15
	s_add_u32 s6, s100, s4
	s_addc_u32 s7, s101, 0
	global_load_dwordx2 v[124:125], v207, s[6:7]
	s_add_i32 s4, s67, 31
	s_min_i32 s4, s4, s57
	s_lshl_b32 s4, s4, 15
	s_add_u32 s6, s100, s4
	s_addc_u32 s7, s101, 0
	global_load_dwordx2 v[126:127], v207, s[6:7]
.Ls5b_nopf:
	ds_read_b128 v[164:167], v230 offset:0
	ds_read_b128 v[168:171], v230 offset:64
	ds_read_b128 v[156:159], v230 offset:128
	ds_read_b128 v[132:135], v230 offset:192
	ds_read_b32 v56, v232 offset:0
	ds_read_b32 v57, v232 offset:64
	ds_read_b32 v58, v232 offset:128
	ds_read_b32 v59, v232 offset:192
	s_waitcnt lgkmcnt(7)
	v_mfma_f32_16x16x32_bf16 v[250:253], v[164:167], v[208:211], 0
	s_waitcnt lgkmcnt(6)
	v_mfma_f32_16x16x32_bf16 v[250:253], v[168:171], v[212:215], v[250:253]
	s_waitcnt lgkmcnt(5)
	v_mfma_f32_16x16x32_bf16 v[250:253], v[156:159], v[216:219], v[250:253]
	s_waitcnt lgkmcnt(4)
	v_mfma_f32_16x16x32_bf16 v[250:253], v[132:135], v[220:223], v[250:253]
	s_waitcnt lgkmcnt(0)
	s_nop 7
	s_nop 1
	v_fma_f32 v250, v224, v56, v250
	v_fma_f32 v251, v224, v57, v251
	v_fma_f32 v252, v224, v58, v252
	v_fma_f32 v253, v224, v59, v253
	v_mul_f32_e32 v60, 0x3d372713, v250
	v_mul_f32_e32 v172, 0x3d372713, v251
	v_mul_f32_e32 v173, 0x3d372713, v252
	v_mul_f32_e32 v245, 0x3d372713, v253
	v_mul_f32_e32 v60, v250, v60
	v_mul_f32_e32 v172, v251, v172
	v_mul_f32_e32 v173, v252, v173
	v_mul_f32_e32 v245, v253, v245
	v_fma_f32 v60, v250, v60, v250
	v_fma_f32 v172, v251, v172, v251
	v_fma_f32 v173, v252, v173, v252
	v_fma_f32 v245, v253, v245, v253
	v_mul_f32_e32 v60, 0x40135761, v60
	v_mul_f32_e32 v172, 0x40135761, v172
	v_mul_f32_e32 v173, 0x40135761, v173
	v_mul_f32_e32 v245, 0x40135761, v245
	v_exp_f32_e32 v60, v60
	v_exp_f32_e32 v172, v172
	v_exp_f32_e32 v173, v173
	v_exp_f32_e32 v245, v245
	s_nop 0
	v_add_f32_e32 v60, 1.0, v60
	v_add_f32_e32 v172, 1.0, v172
	v_add_f32_e32 v173, 1.0, v173
	v_add_f32_e32 v245, 1.0, v245
	v_rcp_f32_e32 v60, v60
	v_rcp_f32_e32 v172, v172
	v_rcp_f32_e32 v173, v173
	v_rcp_f32_e32 v245, v245
	s_nop 0
	v_fma_f32 v250, -v60, v250, v250
	v_fma_f32 v251, -v172, v251, v251
	v_fma_f32 v252, -v173, v252, v252
	v_fma_f32 v253, -v245, v253, v253
	v_cvt_pk_bf16_f32 v250, v250, 0
	v_cvt_pk_bf16_f32 v251, v251, 0
	v_cvt_pk_bf16_f32 v252, v252, 0
	v_cvt_pk_bf16_f32 v253, v253, 0
	s_cmp_lg_u32 s35, 0
	s_cselect_b32 s4, 0, -1
	s_mov_b32 exec_hi, s4
	global_store_short v233, v250, s[86:87]
	global_store_short v241, v251, s[86:87]
	global_store_short v242, v252, s[86:87]
	global_store_short v243, v253, s[86:87]
	s_mov_b32 exec_hi, -1
	s_cmp_lg_u32 s35, 0
	s_cbranch_scc1 .Ls5b_ep_skip1
	ds_read_b128 v[164:167], v230 offset:4352
	ds_read_b128 v[168:171], v230 offset:4416
	ds_read_b128 v[156:159], v230 offset:4480
	ds_read_b128 v[132:135], v230 offset:4544
	ds_read_b32 v56, v232 offset:1024
	ds_read_b32 v57, v232 offset:1088
	ds_read_b32 v58, v232 offset:1152
	ds_read_b32 v59, v232 offset:1216
	s_waitcnt lgkmcnt(7)
	v_mfma_f32_16x16x32_bf16 v[250:253], v[164:167], v[208:211], 0
	s_waitcnt lgkmcnt(6)
	v_mfma_f32_16x16x32_bf16 v[250:253], v[168:171], v[212:215], v[250:253]
	s_waitcnt lgkmcnt(5)
	v_mfma_f32_16x16x32_bf16 v[250:253], v[156:159], v[216:219], v[250:253]
	s_waitcnt lgkmcnt(4)
	v_mfma_f32_16x16x32_bf16 v[250:253], v[132:135], v[220:223], v[250:253]
	s_waitcnt lgkmcnt(0)
	s_nop 7
	s_nop 1
	v_fma_f32 v250, v224, v56, v250
	v_fma_f32 v251, v224, v57, v251
	v_fma_f32 v252, v224, v58, v252
	v_fma_f32 v253, v224, v59, v253
	v_mul_f32_e32 v60, 0x3d372713, v250
	v_mul_f32_e32 v172, 0x3d372713, v251
	v_mul_f32_e32 v173, 0x3d372713, v252
	v_mul_f32_e32 v245, 0x3d372713, v253
	v_mul_f32_e32 v60, v250, v60
	v_mul_f32_e32 v172, v251, v172
	v_mul_f32_e32 v173, v252, v173
	v_mul_f32_e32 v245, v253, v245
	v_fma_f32 v60, v250, v60, v250
	v_fma_f32 v172, v251, v172, v251
	v_fma_f32 v173, v252, v173, v252
	v_fma_f32 v245, v253, v245, v253
	v_mul_f32_e32 v60, 0x40135761, v60
	v_mul_f32_e32 v172, 0x40135761, v172
	v_mul_f32_e32 v173, 0x40135761, v173
	v_mul_f32_e32 v245, 0x40135761, v245
	v_exp_f32_e32 v60, v60
	v_exp_f32_e32 v172, v172
	v_exp_f32_e32 v173, v173
	v_exp_f32_e32 v245, v245
	s_nop 0
	v_add_f32_e32 v60, 1.0, v60
	v_add_f32_e32 v172, 1.0, v172
	v_add_f32_e32 v173, 1.0, v173
	v_add_f32_e32 v245, 1.0, v245
	v_rcp_f32_e32 v60, v60
	v_rcp_f32_e32 v172, v172
	v_rcp_f32_e32 v173, v173
	v_rcp_f32_e32 v245, v245
	s_nop 0
	v_fma_f32 v250, -v60, v250, v250
	v_fma_f32 v251, -v172, v251, v251
	v_fma_f32 v252, -v173, v252, v252
	v_fma_f32 v253, -v245, v253, v253
	v_cvt_pk_bf16_f32 v250, v250, 0
	v_cvt_pk_bf16_f32 v251, v251, 0
	v_cvt_pk_bf16_f32 v252, v252, 0
	v_cvt_pk_bf16_f32 v253, v253, 0
	global_store_short v233, v250, s[88:89]
	global_store_short v241, v251, s[88:89]
	global_store_short v242, v252, s[88:89]
	global_store_short v243, v253, s[88:89]
